# nt hint also on the mixer's read-once streams (Q fragments, conv cb/cc/cu rows) and on the prologue's PB stores
# speedup vs baseline: 1.0018x; 1.0018x over previous
; __device__ __forceinline__ unsigned cvt_pk_bf16(float lo, float hi) { unsigned r; asm volatile("v_cvt_pk_bf16_f32 %0, %1, %2" : "=v"(r) : "v"(lo), "v"(hi)); return r; }
; __device__ __forceinline__ void prologue(const Args& A, LAS unsigned char* lds) {
;     ...
;     const float* p = A.in[I_P]; bf16_t* pb = (bf16_t*)(A.ws + WS_PB);
;     const size_t n8 = (size_t)DEPTH * MTOK * PLE / 8, stride = (size_t)gridDim.x * 512;
;     for (size_t i = (size_t)blockIdx.x * 512 + tid; i < n8; i += stride) {
;         const f32x4 a = *(const f32x4*)(p + i * 8), b = *(const f32x4*)(p + i * 8 + 4);
;         u32x4 w; w.x = pg8::cvt_pk_bf16(a[0], a[1]); w.y = pg8::cvt_pk_bf16(a[2], a[3]); w.z = pg8::cvt_pk_bf16(b[0], b[1]); w.w = pg8::cvt_pk_bf16(b[2], b[3]);
;         *(u32x4*)(pb + i * 8) = w;
;     }
.LBB0_208:
	global_load_dwordx4 v[8:11], v[4:5], off offset:-16 nt
	global_load_dwordx4 v[12:15], v[4:5], off nt
	v_lshl_add_u64 v[2:3], v[2:3], 0, s[4:5]
	v_cmp_lt_u64_e32 vcc, s[12:13], v[2:3]
	v_lshl_add_u64 v[4:5], v[4:5], 0, s[6:7]
	s_or_b64 s[10:11], vcc, s[10:11]
	s_waitcnt vmcnt(1)
	v_cvt_pk_bf16_f32 v8, v8, v9
	v_cvt_pk_bf16_f32 v9, v10, v11
	s_waitcnt vmcnt(0)
	v_cvt_pk_bf16_f32 v10, v12, v13
	v_cvt_pk_bf16_f32 v11, v14, v15
	global_store_dwordx4 v[6:7], v[8:11], off nt
	v_lshl_add_u64 v[6:7], v[6:7], 0, s[8:9]
	s_andn2_b64 exec, exec, s[10:11]
	s_cbranch_execnz .LBB0_208

; #define LAS __attribute__((address_space(3)))
; __device__ __forceinline__ void mixer_attn(const bf16_t* Z, bf16_t* MIX, int b, int r, LAS unsigned char* lds) {
;     ...
;     const int tid = tid_l, lane = tid & 63, h = __builtin_amdgcn_readfirstlane(tid >> 6), i = lane & 15, g = lane >> 4;
;     LAS unsigned char* wl = lds + h * WREG;
;     LAS const float* btab = (LAS const float*)(wl + BT_OFF);
;     LAS float* ssbuf = (LAS float*)(lds + SSBUF_OFF);
;     const bf16_t* zq = Z + ((size_t)b * SEQ + r * 64) * NIN + h * 64;
;     LAS unsigned char* qlds = wl + Q_OFF + lane * 16;
; #pragma unroll
;     for (int jq = 0; jq < 4; ++jq)
; #pragma unroll
;         for (int dh = 0; dh < 2; ++dh) *(LAS bf16x8*)(qlds + (2 * jq + dh) * 1024) = *(const bf16x8*)((const char*)zq + (size_t)(((16 * jq) * NIN + 32 * dh) * 2) + (unsigned)(i * NIN + 8 * g) * 2u);
;     f32x4 o[4][4]; float mrun[4], lrun[4]; int m0[4];
; #pragma unroll
;     for (int jq = 0; jq < 4; ++jq) { mrun[jq] = -__builtin_inff(); lrun[jq] = 0.f; m0[jq] = 4 * g - min(max(16 * jq + i - 8, 0), 48);
; #pragma unroll
;         for (int dt = 0; dt < 4; ++dt) o[jq][dt] = (f32x4){0.f, 0.f, 0.f, 0.f}; }
;     const int r0 = min(max(r - 4, 0), 56), c0 = 4 * g - i;
;     LAS unsigned char* vrd = wl + (4 * g + (i >> 2)) * VS + 8 * (i & 3);
;     const bf16_t* kbb = Z + ((size_t)b * SEQ) * NIN + h * 64;
;     const bf16_t* kb0 = kbb + (size_t)((r0 + ((0 - r0) & 7)) * 64) * NIN;
;     const unsigned kfo = (unsigned)(i * NIN + 8 * g) * 2u;
;     const unsigned vfo = (unsigned)((lane >> 3) * NIN + 8 * (lane & 7)) * 2u;
;     ...
;     bf16x8 kf[4][2]; u32x4 vc[8];
; #pragma unroll
;     for (int n = 0; n < 8; ++n) vc[n] = LDV(kb0, n);
;     asm volatile("" ::: "memory");
; #pragma unroll
;     for (int kt = 0; kt < 4; ++kt)
; #pragma unroll
;         for (int dh = 0; dh < 2; ++dh) kf[kt][dh] = LDK(kb0, kt, dh);
.LBB0_288:
	s_and_b32 s0, s92, 63
	v_sub_u32_e64 v0, s0, 4 clamp
	v_mov_b32_e32 v44, v232
	v_readfirstlane_b32 s0, v0
	s_min_u32 s0, s0, 56
	s_sub_i32 s85, 0, s0
	s_ashr_i32 s4, s86, 6
	v_readfirstlane_b32 s0, v44
	s_lshr_b32 s1, s0, 6
	s_and_b32 s2, s86, 63
	s_mulk_i32 s1, 0x4d00
	s_ashr_i32 s5, s4, 31
	s_add_i32 s60, s1, 0
	s_lshl_b64 s[88:89], s[4:5], 12
	s_lshl_b32 s1, s2, 6
	s_or_b32 s96, s88, s1
	v_writelane_b32 v255, s1, 34
	s_mul_i32 s1, s89, 0x1800
	s_mul_hi_u32 s5, s96, 0x1800
	s_add_i32 s5, s5, s1
	s_mul_i32 s1, s96, 0x1800
	s_add_u32 s6, s72, s1
	s_addc_u32 s5, s73, s5
	s_andn2_b32 s0, s0, 63
	s_ashr_i32 s1, s0, 31
	v_and_b32_e32 v205, 15, v44
	s_lshl_b64 s[80:81], s[0:1], 1
	s_add_u32 s6, s6, s80
	v_mul_u32_u24_e32 v0, 0x1800, v205
	s_addc_u32 s7, s5, s81
	v_and_or_b32 v156, v44, 48, v0
	v_mov_b32_e32 v157, v193
	v_lshl_add_u64 v[24:25], s[6:7], 0, v[156:157]
	v_add_co_u32_e32 v12, vcc, s3, v24
	global_load_dwordx4 v[0:3], v156, s[6:7] nt
	global_load_dwordx4 v[4:7], v156, s[6:7] offset:64 nt
	v_addc_co_u32_e32 v13, vcc, 0, v25, vcc
	v_add_co_u32_e32 v20, vcc, s78, v24
	global_load_dwordx4 v[8:11], v[12:13], off nt
	s_nop 0
	global_load_dwordx4 v[12:15], v[12:13], off offset:64 nt
	v_addc_co_u32_e32 v21, vcc, 0, v25, vcc
	v_add_co_u32_e32 v28, vcc, s79, v24
	global_load_dwordx4 v[16:19], v[20:21], off nt
	s_nop 0
	global_load_dwordx4 v[20:23], v[20:21], off offset:64 nt
	v_addc_co_u32_e32 v29, vcc, 0, v25, vcc
	global_load_dwordx4 v[24:27], v[28:29], off nt
	s_nop 0
	global_load_dwordx4 v[28:31], v[28:29], off offset:64 nt
	v_sub_u32_e64 v32, s2, 4 clamp
	s_mul_hi_i32 s5, s4, 0x1800000
	v_readfirstlane_b32 s1, v32
	s_mul_i32 s4, s4, 0x1800000
	s_min_u32 s1, s1, 56
	s_add_u32 s4, s72, s4
	s_addc_u32 s5, s73, s5
	s_add_u32 s82, s4, s80
	s_addc_u32 s93, s5, s81
	s_sub_i32 s4, 0, s1
	v_and_b32_e32 v209, 63, v44
	s_and_b32 s4, s4, 7
	v_bfe_u32 v45, v44, 3, 3
	v_lshlrev_b32_e32 v35, 4, v209
	s_add_i32 s4, s4, s1
	v_lshlrev_b32_e32 v34, 3, v44
	v_mul_u32_u24_e32 v37, 0xc00, v45
	v_add_u32_e32 v210, s60, v35
	s_mul_i32 s4, s4, 0x60000
	s_add_u32 s4, s82, s4
	s_addc_u32 s5, s93, 0
	v_mov_b32_e32 v161, v193
	s_mov_b32 s77, 0xc000
	s_mov_b32 s94, 0x24000
	s_mov_b32 s95, 0x3c000
	v_bfe_u32 v32, v44, 2, 4
	s_movk_i32 s6, 0x90
	v_lshrrev_b32_e32 v33, 2, v44
	v_and_b32_e32 v208, 12, v33
	v_sub_u32_e64 v33, v205, 8 clamp
	v_min_u32_e32 v36, 8, v205
	v_and_b32_e32 v46, 24, v34
	v_sub_u32_e32 v47, v208, v33
	v_sub_u32_e32 v49, v208, v36
	v_sub_u32_e32 v48, v208, v205
	v_add_u32_e32 v50, -8, v48
	s_movk_i32 s50, 0xffe0
	v_subrev_u32_e32 v51, 24, v48
	v_subrev_u32_e32 v60, 40, v49
	s_movk_i32 s58, 0xffd0
	s_movk_i32 s44, 0xffef
	v_lshl_add_u32 v211, v48, 2, s60
	v_add_u32_e32 v128, 10, v49
	v_add_u32_e32 v129, 11, v49
	s_mov_b32 s33, 0
	s_mov_b32 s97, s89
	s_sub_i32 s2, s1, s2
	v_cmp_lt_u32_e64 s[10:11], s44, v47
	v_cmp_gt_u32_e64 s[18:19], 16, v50
	v_cmp_lt_u32_e64 s[26:27], s44, v50
	v_cmp_lt_u32_e64 s[44:45], s44, v51
	v_mov_b32_e32 v192, 0xff800000
	v_mov_b32_e32 v216, 0xff800000
	v_mov_b32_e32 v215, 0xff800000
	s_waitcnt vmcnt(7)
	ds_write_b128 v210, v[0:3] offset:11520
	s_waitcnt vmcnt(6)
	ds_write_b128 v210, v[4:7] offset:12544
	s_waitcnt vmcnt(5)
	ds_write_b128 v210, v[8:11] offset:13568
	s_waitcnt vmcnt(4)
	ds_write_b128 v210, v[12:15] offset:14592
	s_waitcnt vmcnt(3)
	ds_write_b128 v210, v[16:19] offset:15616
	s_waitcnt vmcnt(2)
	ds_write_b128 v210, v[20:23] offset:16640
	s_waitcnt vmcnt(1)
	ds_write_b128 v210, v[24:27] offset:17664
	s_waitcnt vmcnt(0)
	ds_write_b128 v210, v[28:31] offset:18688
	v_and_or_b32 v0, v34, 56, v37
	v_lshlrev_b32_e32 v160, 1, v0
	v_lshl_add_u64 v[0:1], s[4:5], 0, v[160:161]
	v_add_co_u32_e32 v2, vcc, s77, v0
	v_mov_b32_e32 v16, 0
	s_nop 0
	v_addc_co_u32_e32 v3, vcc, 0, v1, vcc
	v_add_co_u32_e32 v4, vcc, s3, v0
	v_mov_b32_e32 v214, 0xff800000
	s_nop 0
	v_addc_co_u32_e32 v5, vcc, 0, v1, vcc
	global_load_dwordx4 v[96:99], v[2:3], off offset:2048
	global_load_dwordx4 v[100:103], v[4:5], off offset:2048
	v_add_co_u32_e32 v2, vcc, s94, v0
	v_mov_b32_e32 v17, v16
	s_nop 0
	v_addc_co_u32_e32 v3, vcc, 0, v1, vcc
	v_add_co_u32_e32 v4, vcc, s78, v0
	v_mov_b32_e32 v18, v16
	s_nop 0
	v_addc_co_u32_e32 v5, vcc, 0, v1, vcc
	global_load_dwordx4 v[108:111], v[2:3], off offset:2048
	global_load_dwordx4 v[112:115], v[4:5], off offset:2048
	v_add_co_u32_e32 v2, vcc, s95, v0
	v_mov_b32_e32 v19, v16
	s_nop 0
	v_addc_co_u32_e32 v3, vcc, 0, v1, vcc
	v_add_co_u32_e32 v4, vcc, s79, v0
	v_mov_b32_e32 v24, v16
	s_nop 0
	v_addc_co_u32_e32 v5, vcc, 0, v1, vcc
	v_add_co_u32_e32 v0, vcc, s99, v0
	global_load_dwordx4 v[116:119], v[2:3], off offset:2048
	global_load_dwordx4 v[120:123], v[4:5], off offset:2048
	v_addc_co_u32_e32 v1, vcc, 0, v1, vcc
	global_load_dwordx4 v[104:107], v160, s[4:5] offset:2048
	global_load_dwordx4 v[124:127], v[0:1], off offset:2048
	v_mov_b32_e32 v0, s60
	v_mad_u32_u24 v4, v32, s6, v0
	v_lshl_add_u64 v[0:1], s[4:5], 0, v[156:157]
	v_add_co_u32_e32 v2, vcc, s3, v0
	global_load_dwordx4 v[40:43], v156, s[4:5] offset:1024
	global_load_dwordx4 v[36:39], v156, s[4:5] offset:1088
	v_addc_co_u32_e32 v3, vcc, 0, v1, vcc
	global_load_dwordx4 v[32:35], v[2:3], off offset:1024
	global_load_dwordx4 v[92:95], v[2:3], off offset:1088
	v_add_co_u32_e32 v2, vcc, s78, v0
	v_add_u32_e32 v213, v4, v46
	s_nop 0
	v_addc_co_u32_e32 v3, vcc, 0, v1, vcc
	v_add_co_u32_e32 v0, vcc, s79, v0
	global_load_dwordx4 v[20:23], v[2:3], off offset:1024
	global_load_dwordx4 v[56:59], v[2:3], off offset:1088
	v_addc_co_u32_e32 v1, vcc, 0, v1, vcc
	global_load_dwordx4 v[80:83], v[0:1], off offset:1024
	global_load_dwordx4 v[52:55], v[0:1], off offset:1088
; #define LAS __attribute__((address_space(3)))
; __device__ __forceinline__ void mixer_attn(const bf16_t* Z, bf16_t* MIX, int b, int r, LAS unsigned char* lds) {
;     ...
;     f32x4 o[4][4]; float mrun[4], lrun[4]; int m0[4];
; #pragma unroll
;     for (int jq = 0; jq < 4; ++jq) { mrun[jq] = -__builtin_inff(); lrun[jq] = 0.f; m0[jq] = 4 * g - min(max(16 * jq + i - 8, 0), 48);
; #pragma unroll
;         for (int dt = 0; dt < 4; ++dt) o[jq][dt] = (f32x4){0.f, 0.f, 0.f, 0.f}; }
;     const int r0 = min(max(r - 4, 0), 56), c0 = 4 * g - i;
;     LAS unsigned char* vrd = wl + (4 * g + (i >> 2)) * VS + 8 * (i & 3);
;     const bf16_t* kbb = Z + ((size_t)b * SEQ) * NIN + h * 64;
;     const bf16_t* kb0 = kbb + (size_t)((r0 + ((0 - r0) & 7)) * 64) * NIN;
;     const unsigned kfo = (unsigned)(i * NIN + 8 * g) * 2u;
;     const unsigned vfo = (unsigned)((lane >> 3) * NIN + 8 * (lane & 7)) * 2u;
;     ...
;     bf16x8 kf[4][2]; u32x4 vc[8];
; #pragma unroll
;     for (int n = 0; n < 8; ++n) vc[n] = LDV(kb0, n);
;     asm volatile("" ::: "memory");
; #pragma unroll
;     for (int kt = 0; kt < 4; ++kt)
; #pragma unroll
;         for (int dh = 0; dh < 2; ++dh) kf[kt][dh] = LDK(kb0, kt, dh);
;     asm volatile("" ::: "memory");
; #pragma unroll 1
;     for (int kr = 0; kr < 8; ++kr) {
;         const int krow = r0 + ((kr - r0) & 7);
;         const bf16_t* kbn = kbb + (size_t)((r0 + ((min(kr + 1, 7) - r0) & 7)) * 64) * NIN;
; #pragma unroll
;         for (int n = 0; n < 8; ++n) { const int ch = lane + 64 * n; *(LAS u32x4*)(wl + (ch >> 3) * VS + 16 * (ch & 7)) = vc[n]; }
;         asm volatile("" ::: "memory");
; #pragma unroll
;         for (int n = 0; n < 8; ++n) vc[n] = LDV(kbn, n);
;         asm volatile("" ::: "memory");
;         LAS const float* brow = btab + (krow - r + 7) * 31 - 1 + c0;
;         bf16x8 pf[6];
;         bf16x8 dummy;
;         f32x4 sA[3], sB[3]; float bA[3][4], bB[3][4];
;         qk<0>(kf, qlds, brow, sA, bA);
	v_add_u32_e32 v1, 1, v47
	v_cmp_gt_u32_e64 s[4:5], 16, v1
	v_add_u32_e32 v1, 2, v47
	v_cmp_gt_u32_e64 s[6:7], 16, v1
	v_add_u32_e32 v1, 3, v47
	v_cmp_gt_u32_e64 s[8:9], 16, v1
	v_add_u32_e32 v1, 17, v47
	v_cmp_gt_u32_e64 s[12:13], 16, v1
	v_add_u32_e32 v1, 18, v47
	v_cmp_gt_u32_e64 s[14:15], 16, v1
	v_add_u32_e32 v1, 19, v47
	v_cmp_gt_u32_e64 s[16:17], 16, v1
	v_add_u32_e32 v1, -7, v48
	v_cmp_gt_u32_e64 s[20:21], 16, v1
	v_add_u32_e32 v1, -6, v48
	v_cmp_gt_u32_e64 s[22:23], 16, v1
	v_add_u32_e32 v1, -5, v48
	v_cmp_gt_u32_e64 s[24:25], 16, v1
	v_add_u32_e32 v1, 9, v48
	v_cmp_gt_u32_e64 s[28:29], 16, v1
	v_add_u32_e32 v1, 10, v48
	v_cmp_gt_u32_e64 s[30:31], 16, v1
	v_add_u32_e32 v1, 11, v48
	v_cmp_gt_u32_e64 s[34:35], 16, v1
	v_and_b32_e32 v1, -16, v50
	v_cmp_eq_u32_e64 s[36:37], s50, v1
	v_add_u32_e32 v1, 25, v48
	v_cmp_gt_u32_e64 s[38:39], 16, v1
	v_add_u32_e32 v1, 26, v48
	v_cmp_gt_u32_e64 s[40:41], 16, v1
	v_add_u32_e32 v1, 27, v48
	v_cmp_gt_u32_e64 s[42:43], 16, v1
	v_and_b32_e32 v1, -16, v51
	v_lshlrev_b32_e32 v0, 4, v44
	v_cmp_eq_u32_e64 s[46:47], s50, v1
	v_cmp_eq_u32_e64 s[48:49], s58, v1
	v_and_b32_e32 v1, -16, v60
	v_add_u32_e32 v2, -7, v49
	v_and_b32_e32 v0, 0x70, v0
	v_cmp_eq_u32_e64 s[50:51], s50, v1
	v_cmp_gt_u32_e64 s[52:53], 16, v2
	v_add_u32_e32 v2, -6, v49
	v_cmp_eq_u32_e64 s[58:59], s58, v1
	v_add_u32_e32 v1, 9, v49
	v_add_u32_e32 v0, s60, v0
	v_cmp_gt_u32_e64 s[54:55], 16, v2
	v_add_u32_e32 v2, -5, v49
	v_cmp_gt_u32_e64 s[60:61], 16, v1
	v_mul_u32_u24_e32 v1, 0x90, v45
	v_cmp_gt_u32_e32 vcc, 16, v47
	v_cmp_gt_u32_e64 s[56:57], 16, v2
	v_add_u32_e32 v212, v0, v1
	v_mov_b32_e32 v25, v16
	v_mov_b32_e32 v26, v16
	v_mov_b32_e32 v27, v16
	v_mov_b32_e32 v28, v16
	v_mov_b32_e32 v29, v16
	v_mov_b32_e32 v30, v16
	v_mov_b32_e32 v31, v16
	v_mov_b32_e32 v44, v16
	v_mov_b32_e32 v45, v16
	v_mov_b32_e32 v46, v16
	v_mov_b32_e32 v47, v16
	v_mov_b32_e32 v60, v16
	v_mov_b32_e32 v61, v16
	v_mov_b32_e32 v62, v16
	v_mov_b32_e32 v63, v16
	v_mov_b32_e32 v64, v16
	v_mov_b32_e32 v65, v16
	v_mov_b32_e32 v66, v16
	v_mov_b32_e32 v67, v16
	v_mov_b32_e32 v72, v16
	v_mov_b32_e32 v73, v16
	v_mov_b32_e32 v74, v16
	v_mov_b32_e32 v75, v16
	v_mov_b32_e32 v84, v16
	v_mov_b32_e32 v85, v16
	v_mov_b32_e32 v86, v16
	v_mov_b32_e32 v87, v16
	v_mov_b32_e32 v88, v16
	v_mov_b32_e32 v89, v16
	v_mov_b32_e32 v90, v16
	v_mov_b32_e32 v91, v16
	v_mov_b32_e32 v76, v16
	v_mov_b32_e32 v77, v16
	v_mov_b32_e32 v78, v16
	v_mov_b32_e32 v79, v16
	v_mov_b32_e32 v68, v16
	v_mov_b32_e32 v69, v16
	v_mov_b32_e32 v70, v16
	v_mov_b32_e32 v71, v16
	v_mov_b32_e32 v48, v16
	v_mov_b32_e32 v49, v16
	v_mov_b32_e32 v50, v16
	v_mov_b32_e32 v51, v16
	v_mov_b32_e32 v12, v16
	v_mov_b32_e32 v13, v16
	v_mov_b32_e32 v14, v16
	v_mov_b32_e32 v15, v16
	v_mov_b32_e32 v8, v16
	v_mov_b32_e32 v9, v16
	v_mov_b32_e32 v10, v16
	v_mov_b32_e32 v11, v16
	v_mov_b32_e32 v4, v16
	v_mov_b32_e32 v5, v16
	v_mov_b32_e32 v6, v16
	v_mov_b32_e32 v7, v16
	v_mov_b32_e32 v0, v16
	v_mov_b32_e32 v1, v16
	v_mov_b32_e32 v2, v16
	v_mov_b32_e32 v3, v16
	v_mov_b32_e32 v158, v16
	v_mov_b32_e32 v159, v16
	v_mov_b32_e32 v162, v16
	v_mov_b32_e32 v163, v16
	v_cmp_gt_u32_e64 s[62:63], 16, v128
	v_cmp_gt_u32_e64 s[64:65], 16, v129
.LBB0_289:
	s_add_i32 s84, s33, 1
	s_min_u32 s67, s84, 7
	s_sub_i32 s67, s67, s1
	s_and_b32 s67, s67, 7
	s_add_i32 s67, s67, s1
	s_add_i32 s66, s85, s33
	s_mul_i32 s67, s67, 0x60000
	s_add_u32 s68, s82, s67
	s_addc_u32 s69, s93, 0
	s_waitcnt vmcnt(9)
	ds_write_b128 v212, v[104:107]
	ds_write_b128 v212, v[96:99] offset:1152
	ds_write_b128 v212, v[100:103] offset:2304
	ds_write_b128 v212, v[108:111] offset:3456
	ds_write_b128 v212, v[112:115] offset:4608
	ds_write_b128 v212, v[116:119] offset:5760
	ds_write_b128 v212, v[120:123] offset:6912
	s_waitcnt vmcnt(8)
	ds_write_b128 v212, v[124:127] offset:8064
	s_and_b32 s66, s66, 7
	v_lshl_add_u64 v[96:97], s[68:69], 0, v[160:161]
	s_add_i32 s76, s2, s66
	v_lshl_add_u64 v[128:129], s[68:69], 0, v[156:157]
	v_add_co_u32_e64 v98, s[66:67], s77, v96
	v_add_co_u32_e64 v100, s[68:69], s3, v96
	s_nop 0
	v_addc_co_u32_e64 v99, s[66:67], 0, v97, s[66:67]
	v_addc_co_u32_e64 v101, s[68:69], 0, v97, s[68:69]
	v_add_co_u32_e64 v108, s[70:71], s94, v96
	v_add_co_u32_e64 v112, s[72:73], s78, v96
	v_add_co_u32_e64 v116, s[74:75], s95, v96
	v_add_co_u32_e64 v120, s[66:67], s79, v96
	v_add_co_u32_e64 v124, s[68:69], s99, v96
	v_addc_co_u32_e64 v109, s[70:71], 0, v97, s[70:71]
	v_addc_co_u32_e64 v113, s[72:73], 0, v97, s[72:73]
	v_addc_co_u32_e64 v117, s[74:75], 0, v97, s[74:75]
	v_addc_co_u32_e64 v121, s[66:67], 0, v97, s[66:67]
	v_addc_co_u32_e64 v125, s[66:67], 0, v97, s[68:69]
	global_load_dwordx4 v[104:107], v[96:97], off offset:2048
	s_nop 0
	global_load_dwordx4 v[96:99], v[98:99], off offset:2048
	s_nop 0
	global_load_dwordx4 v[100:103], v[100:101], off offset:2048
	s_nop 0
	global_load_dwordx4 v[108:111], v[108:109], off offset:2048
	s_nop 0
	global_load_dwordx4 v[112:115], v[112:113], off offset:2048
	s_nop 0
	global_load_dwordx4 v[116:119], v[116:117], off offset:2048
	s_nop 0
	global_load_dwordx4 v[120:123], v[120:121], off offset:2048
	s_nop 0
	global_load_dwordx4 v[124:127], v[124:125], off offset:2048
	ds_read_b128 v[132:135], v210 offset:11520
	s_mulk_i32 s76, 0x7c
	v_add_u32_e32 v142, s76, v211
	v_add_u32_e32 v165, 0x2860, v142
	v_add_u32_e32 v200, 0x28a0, v142
	v_add_u32_e32 v202, 0x28a8, v142
	s_waitcnt vmcnt(15) lgkmcnt(0)
	v_mfma_f32_16x16x32_bf16 v[138:141], v[40:43], v[132:135], 0
	v_add_u32_e32 v174, 0x28e0, v142
	v_add_u32_e32 v176, 0x28e8, v142
	v_add_u32_e32 v194, 0x2868, v142
	ds_read_b128 v[142:145], v210 offset:13568
	ds_read_b128 v[146:149], v210 offset:12544
	ds_read_b128 v[150:153], v210 offset:14592
	s_waitcnt vmcnt(13)
; __device__ __forceinline__ bf16x8 packp(const f32x4 a, const f32x4 b) { u32x4 w; w.x = pg8::cvt_pk_bf16(a[0], a[1]); w.y = pg8::cvt_pk_bf16(a[2], a[3]); w.z = pg8::cvt_pk_bf16(b[0], b[1]); w.w = pg8::cvt_pk_bf16(b[2], b[3]); return __builtin_bit_cast(bf16x8, w); }
; template <int JQ> __device__ __forceinline__ void sm(f32x4 (&s)[3], float (&bb)[3][4], int m0, float& mrun, float& lrun, f32x4 (&o)[4], bf16x8& pA, bf16x8& pB) {
;     constexpr int T0 = QTiles<JQ>::T0, NT = QTiles<JQ>::NT;
;     const float NEG = -__builtin_inff();
;     if (NT == 2) asm volatile("" : "+v"(bb[0][0]), "+v"(bb[0][1]), "+v"(bb[0][2]), "+v"(bb[0][3]), "+v"(bb[1][0]), "+v"(bb[1][1]), "+v"(bb[1][2]), "+v"(bb[1][3]));
;     else asm volatile("" : "+v"(bb[0][0]), "+v"(bb[0][1]), "+v"(bb[0][2]), "+v"(bb[0][3]), "+v"(bb[1][0]), "+v"(bb[1][1]), "+v"(bb[1][2]), "+v"(bb[1][3]), "+v"(bb[2][0]), "+v"(bb[2][1]), "+v"(bb[2][2]), "+v"(bb[2][3]));
;     float mx = NEG;
; #pragma unroll
;     for (int t = 0; t < NT; ++t)
; #pragma unroll
;         for (int e = 0; e < 4; ++e) { const bool valid = (unsigned)(m0 + 16 * (T0 + t) + e) < 16u; const float v = s[t][e] + bb[t][e]; s[t][e] = valid ? v : NEG; mx = fmaxf(mx, s[t][e]); }
;     mx = xrow16_max(mx);
;     const float mnew = fmaxf(mrun, mx), alpha = __builtin_amdgcn_exp2f(mrun - mnew);
;     mrun = mnew;
;     float ps = 0.f;
; #pragma unroll
;     for (int t = 0; t < NT; ++t)
; #pragma unroll
;         for (int e = 0; e < 4; ++e) { const float p = __builtin_amdgcn_exp2f(s[t][e] - mnew); s[t][e] = p; ps += p; }
;     lrun = lrun * alpha + ps;
; #pragma unroll
;     for (int dt = 0; dt < 4; ++dt) o[dt] *= alpha;
;     const f32x4 zz = {0.f, 0.f, 0.f, 0.f};
;     if (JQ == 0) { pA = packp(s[0], s[1]); }
;     else if (JQ == 1) { pA = packp(s[0], s[1]); pB = packp(s[2], zz); }
;     else if (JQ == 2) { pA = packp(zz, s[0]); pB = packp(s[1], s[2]); }
;     else { pB = packp(s[0], s[1]); }
; }
; __device__ __forceinline__ void mixer_attn(const bf16_t* Z, bf16_t* MIX, int b, int r, LAS unsigned char* lds) {
;     ...
;         qk<0>(kf, qlds, brow, sA, bA);
;         qk<1>(kf, qlds, brow, sB, bB);
;         sm<0>(sA, bA, m0[0], mrun[0], lrun[0], o[0], pf[0], dummy);
;         qk<2>(kf, qlds, brow, sA, bA);
;         sm<1>(sB, bB, m0[1], mrun[1], lrun[1], o[1], pf[1], pf[2]);
	v_mfma_f32_16x16x32_bf16 v[132:135], v[32:35], v[132:135], 0
	ds_read2_b32 v[154:155], v200 offset1:1
	ds_read2_b32 v[170:171], v202 offset1:1
	ds_read2_b32 v[172:173], v174 offset1:1
	ds_read2_b32 v[180:181], v165 offset1:1
	ds_read2_b32 v[186:187], v176 offset1:1
	ds_read2_b32 v[188:189], v194 offset1:1
	v_add_co_u32_e64 v130, s[70:71], s3, v128
	s_waitcnt lgkmcnt(7)
	v_mfma_f32_16x16x32_bf16 v[138:141], v[36:39], v[146:149], v[138:141]
	s_waitcnt lgkmcnt(3)
	v_mov_b32_e32 v175, v173
	v_mov_b32_e32 v177, v154
	s_waitcnt lgkmcnt(1)
	v_mov_b32_e32 v178, v187
	v_mfma_f32_16x16x32_bf16 v[40:43], v[40:43], v[142:145], 0
	v_mov_b32_e32 v179, v170
	v_mov_b32_e32 v182, v172
	v_mov_b32_e32 v183, v186
	v_mfma_f32_16x16x32_bf16 v[166:169], v[32:35], v[142:145], 0
	v_mov_b32_e32 v195, v171
	v_add_co_u32_e64 v184, s[72:73], s78, v128
	s_waitcnt vmcnt(8)
	v_mfma_f32_16x16x32_bf16 v[142:145], v[20:23], v[142:145], 0
	v_add_co_u32_e64 v136, s[74:75], s79, v128
	v_addc_co_u32_e64 v131, s[66:67], 0, v129, s[70:71]
	v_mfma_f32_16x16x32_bf16 v[132:135], v[92:95], v[146:149], v[132:135]
	v_mov_b32_e32 v146, v155
	v_mov_b32_e32 v147, v171
	v_mfma_f32_16x16x32_bf16 v[36:39], v[36:39], v[150:153], v[40:43]
	v_add_f32_e32 v138, v138, v177
	v_add_f32_e32 v139, v139, v146
	v_add_f32_e32 v140, v140, v179
	v_add_f32_e32 v141, v141, v147
	v_cndmask_b32_e32 v138, v235, v138, vcc
	v_cndmask_b32_e64 v139, v235, v139, s[4:5]
	v_mfma_f32_16x16x32_bf16 v[40:43], v[92:95], v[150:153], v[166:169]
	v_add_f32_e32 v132, v132, v182
	v_add_f32_e32 v133, v133, v175
	v_cndmask_b32_e64 v140, v235, v140, s[6:7]
	s_waitcnt vmcnt(10)
	v_mfma_f32_16x16x32_bf16 v[148:151], v[56:59], v[150:153], v[142:145]
	v_cndmask_b32_e64 v141, v235, v141, s[8:9]
	v_add_f32_e32 v134, v134, v183
	v_add_f32_e32 v135, v135, v178
	v_max3_f32 v142, v138, s98, v139
	v_cndmask_b32_e64 v132, v235, v132, s[10:11]
	v_cndmask_b32_e64 v133, v235, v133, s[12:13]
	v_max3_f32 v142, v142, v140, v141
	v_cndmask_b32_e64 v134, v235, v134, s[14:15]
	v_cndmask_b32_e64 v135, v235, v135, s[16:17]
	v_max3_f32 v142, v142, v132, v133
	v_max3_f32 v142, v142, v134, v135
	v_mov_b32_e32 v143, v142
	s_nop 1
	v_permlane16_swap_b32_e32 v142, v143
	v_max_f32_e32 v143, v143, v143
	v_max_f32_e32 v142, v142, v142
	v_max_f32_e32 v142, v142, v143
	v_mov_b32_e32 v143, v142
	s_nop 1
	v_permlane32_swap_b32_e32 v142, v143
	v_max3_f32 v142, v214, v142, v143
	v_sub_f32_e32 v143, v214, v142
	v_sub_f32_e32 v138, v138, v142
	v_sub_f32_e32 v139, v139, v142
	v_sub_f32_e32 v140, v140, v142
	v_sub_f32_e32 v141, v141, v142
	v_sub_f32_e32 v132, v132, v142
	v_sub_f32_e32 v133, v133, v142
	v_sub_f32_e32 v134, v134, v142
	v_sub_f32_e32 v135, v135, v142
	v_mov_b32_e32 v214, v142
	v_exp_f32_e32 v142, v143
	s_waitcnt lgkmcnt(0)
	v_mov_b32_e32 v166, v188
	v_mov_b32_e32 v168, v173
	v_exp_f32_e32 v183, v138
	v_exp_f32_e32 v179, v139
	v_exp_f32_e32 v177, v140
	v_exp_f32_e32 v175, v141
	v_exp_f32_e32 v169, v132
	v_exp_f32_e32 v173, v133
	v_exp_f32_e32 v171, v134
	v_exp_f32_e32 v167, v135
	v_cvt_pk_bf16_f32 v144, v183, v179
	v_cvt_pk_bf16_f32 v145, v177, v175
	v_cvt_pk_bf16_f32 v146, v169, v173
	v_cvt_pk_bf16_f32 v147, v171, v167
	ds_read_b128 v[132:135], v210 offset:15616
	ds_read_b128 v[138:141], v210 offset:16640
	ds_read2_b32 v[190:191], v165 offset1:1
	ds_read2_b32 v[206:207], v200 offset1:1
	ds_read2_b32 v[230:231], v202 offset1:1
	ds_read2_b32 v[246:247], v174 offset1:1
	ds_read2_b32 v[248:249], v194 offset1:1
	ds_read2_b32 v[250:251], v176 offset1:1
	v_pk_mul_f32 v[50:51], v[50:51], v[142:143] op_sel_hi:[1,0]
	v_add_f32_e32 v36, v36, v180
	v_add_f32_e32 v37, v37, v181
	v_pk_mul_f32 v[48:49], v[48:49], v[142:143] op_sel_hi:[1,0]
	v_pk_mul_f32 v[70:71], v[70:71], v[142:143] op_sel_hi:[1,0]
	v_pk_mul_f32 v[68:69], v[68:69], v[142:143] op_sel_hi:[1,0]
	v_pk_mul_f32 v[78:79], v[78:79], v[142:143] op_sel_hi:[1,0]
	v_pk_mul_f32 v[76:77], v[76:77], v[142:143] op_sel_hi:[1,0]
	v_pk_mul_f32 v[90:91], v[90:91], v[142:143] op_sel_hi:[1,0]
	v_pk_mul_f32 v[88:89], v[88:89], v[142:143] op_sel_hi:[1,0]
	v_add_f32_e32 v38, v38, v166
	v_add_f32_e32 v39, v39, v189
	v_add_f32_e32 v40, v40, v154
	v_add_f32_e32 v143, v148, v172
	v_add_f32_e32 v148, v149, v168
	v_add_f32_e32 v149, v150, v186
	v_add_f32_e32 v150, v151, v187
	v_cndmask_b32_e64 v151, v235, v36, s[18:19]
	v_cndmask_b32_e64 v152, v235, v37, s[20:21]
	s_waitcnt lgkmcnt(7)
	v_mfma_f32_16x16x32_bf16 v[32:35], v[32:35], v[132:135], 0
	v_add_f32_e32 v41, v41, v155
	v_cndmask_b32_e64 v153, v235, v38, s[22:23]
	v_cndmask_b32_e64 v154, v235, v39, s[24:25]
	v_cndmask_b32_e64 v155, v235, v40, s[26:27]
	v_max3_f32 v40, v151, s98, v152
	v_add_f32_e32 v42, v42, v170
	v_add_f32_e32 v43, v43, v195
	v_cndmask_b32_e64 v166, v235, v41, s[28:29]
	v_max3_f32 v40, v40, v153, v154
	v_cndmask_b32_e64 v168, v235, v42, s[30:31]
	v_cndmask_b32_e64 v170, v235, v43, s[34:35]
	v_max3_f32 v172, v40, v155, v166
	v_cndmask_b32_e64 v143, v235, v143, s[36:37]
	v_cndmask_b32_e64 v148, v235, v148, s[38:39]
	s_waitcnt lgkmcnt(6)
	v_mfma_f32_16x16x32_bf16 v[186:189], v[92:95], v[138:141], v[32:35]
	v_cndmask_b32_e64 v149, v235, v149, s[40:41]
	v_cndmask_b32_e64 v150, v235, v150, s[42:43]
	s_waitcnt lgkmcnt(1)
	v_mov_b32_e32 v204, v248
	v_max3_f32 v32, v172, v168, v170
	v_max3_f32 v32, v32, v143, v148
	v_max3_f32 v32, v32, v149, v150
	v_mov_b32_e32 v33, v32
	s_nop 1
	v_permlane16_swap_b32_e32 v32, v33
	v_max_f32_e32 v33, v33, v33
	v_max_f32_e32 v32, v32, v32
	v_max_f32_e32 v32, v32, v33
	v_mov_b32_e32 v33, v32
	s_nop 1
	v_permlane32_swap_b32_e32 v32, v33
	v_mfma_f32_16x16x32_bf16 v[36:39], v[20:23], v[132:135], 0
	v_max3_f32 v32, v215, v32, v33
	v_sub_f32_e32 v33, v215, v32
	v_exp_f32_e32 v180, v33
	s_waitcnt vmcnt(9)
; template <int JQ> __device__ __forceinline__ void sm(f32x4 (&s)[3], float (&bb)[3][4], int m0, float& mrun, float& lrun, f32x4 (&o)[4], bf16x8& pA, bf16x8& pB) {
;     constexpr int T0 = QTiles<JQ>::T0, NT = QTiles<JQ>::NT;
;     const float NEG = -__builtin_inff();
;     if (NT == 2) asm volatile("" : "+v"(bb[0][0]), "+v"(bb[0][1]), "+v"(bb[0][2]), "+v"(bb[0][3]), "+v"(bb[1][0]), "+v"(bb[1][1]), "+v"(bb[1][2]), "+v"(bb[1][3]));
;     else asm volatile("" : "+v"(bb[0][0]), "+v"(bb[0][1]), "+v"(bb[0][2]), "+v"(bb[0][3]), "+v"(bb[1][0]), "+v"(bb[1][1]), "+v"(bb[1][2]), "+v"(bb[1][3]), "+v"(bb[2][0]), "+v"(bb[2][1]), "+v"(bb[2][2]), "+v"(bb[2][3]));
;     float mx = NEG;
; #pragma unroll
;     for (int t = 0; t < NT; ++t)
; #pragma unroll
;         for (int e = 0; e < 4; ++e) { const bool valid = (unsigned)(m0 + 16 * (T0 + t) + e) < 16u; const float v = s[t][e] + bb[t][e]; s[t][e] = valid ? v : NEG; mx = fmaxf(mx, s[t][e]); }
;     mx = xrow16_max(mx);
;     const float mnew = fmaxf(mrun, mx), alpha = __builtin_amdgcn_exp2f(mrun - mnew);
;     mrun = mnew;
;     float ps = 0.f;
; #pragma unroll
;     for (int t = 0; t < NT; ++t)
; #pragma unroll
;         for (int e = 0; e < 4; ++e) { const float p = __builtin_amdgcn_exp2f(s[t][e] - mnew); s[t][e] = p; ps += p; }
;     lrun = lrun * alpha + ps;
; #pragma unroll
;     for (int dt = 0; dt < 4; ++dt) o[dt] *= alpha;
;     const f32x4 zz = {0.f, 0.f, 0.f, 0.f};
;     if (JQ == 0) { pA = packp(s[0], s[1]); }
;     else if (JQ == 1) { pA = packp(s[0], s[1]); pB = packp(s[2], zz); }
;     else if (JQ == 2) { pA = packp(zz, s[0]); pB = packp(s[1], s[2]); }
;     else { pB = packp(s[0], s[1]); }
; }
; __device__ __forceinline__ void mixer_attn(const bf16_t* Z, bf16_t* MIX, int b, int r, LAS unsigned char* lds) {
;     ...
;         qk<2>(kf, qlds, brow, sA, bA);
;         sm<1>(sB, bB, m0[1], mrun[1], lrun[1], o[1], pf[1], pf[2]);
;         qk<3>(kf, qlds, brow, sB, bB);
;         asm volatile("" ::: "memory");
; #pragma unroll
;         for (int kt = 0; kt < 4; ++kt)
; #pragma unroll
;             for (int dh = 0; dh < 2; ++dh) kf[kt][dh] = LDK(kbn, kt, dh);
;         asm volatile("" ::: "memory");
;         sm<2>(sA, bA, m0[2], mrun[2], lrun[2], o[2], pf[3], pf[4]);
	v_mfma_f32_16x16x32_bf16 v[40:43], v[80:83], v[132:135], 0
	v_sub_f32_e32 v34, v151, v32
	v_sub_f32_e32 v35, v152, v32
	v_sub_f32_e32 v92, v149, v32
	v_mfma_f32_16x16x32_bf16 v[218:221], v[56:59], v[138:141], v[36:39]
	v_sub_f32_e32 v93, v150, v32
	v_mov_b32_e32 v215, v32
	v_mov_b32_e32 v217, v247
	s_waitcnt vmcnt(8)
	v_mfma_f32_16x16x32_bf16 v[222:225], v[52:55], v[138:141], v[40:43]
	v_sub_f32_e32 v36, v153, v32
	v_sub_f32_e32 v37, v154, v32
	v_sub_f32_e32 v38, v155, v32
	v_sub_f32_e32 v39, v166, v32
	v_sub_f32_e32 v40, v168, v32
	v_sub_f32_e32 v41, v170, v32
	v_sub_f32_e32 v42, v143, v32
	v_sub_f32_e32 v43, v148, v32
	v_exp_f32_e32 v32, v34
	s_waitcnt lgkmcnt(0)
	v_mov_b32_e32 v237, v251
	v_exp_f32_e32 v247, v35
	v_exp_f32_e32 v248, v36
	v_exp_f32_e32 v251, v37
	v_exp_f32_e32 v182, v38
	v_exp_f32_e32 v178, v39
	v_exp_f32_e32 v176, v40
	v_exp_f32_e32 v174, v41
	v_exp_f32_e32 v168, v42
	v_exp_f32_e32 v172, v43
	v_exp_f32_e32 v170, v92
	v_exp_f32_e32 v166, v93
	v_pk_mul_f32 v[154:155], v[86:87], v[180:181] op_sel_hi:[1,0]
	v_pk_mul_f32 v[152:153], v[84:85], v[180:181] op_sel_hi:[1,0]
	v_cvt_pk_bf16_f32 v84, v32, v247
	v_cvt_pk_bf16_f32 v85, v248, v251
	v_cvt_pk_bf16_f32 v86, v182, v178
	v_cvt_pk_bf16_f32 v87, v176, v174
	v_cvt_pk_bf16_f32 v92, v168, v172
	v_cvt_pk_bf16_f32 v93, v170, v166
	v_cvt_pk_bf16_f32 v94, v193, v193
	v_cvt_pk_bf16_f32 v95, v193, v193
	ds_read_b128 v[226:229], v210 offset:17664
	ds_read_b128 v[238:241], v210 offset:18688
	ds_read2_b32 v[252:253], v165 offset1:1
	ds_read2_b32 v[194:195], v194 offset1:1
	ds_read2_b32 v[200:201], v200 offset1:1
	ds_read2_b32 v[202:203], v202 offset1:1
	s_waitcnt lgkmcnt(5)
	v_mfma_f32_16x16x32_bf16 v[242:245], v[20:23], v[226:229], 0
	v_addc_co_u32_e64 v185, s[66:67], 0, v129, s[72:73]
	v_addc_co_u32_e64 v137, s[66:67], 0, v129, s[74:75]
	v_mfma_f32_16x16x32_bf16 v[80:83], v[80:83], v[226:229], 0
	v_mul_f32_e64 v150, v74, v180
	v_mul_f32_e64 v151, v75, v180
	v_pk_mul_f32 v[148:149], v[72:73], v[180:181] op_sel_hi:[1,0]
	v_pk_mul_f32 v[74:75], v[66:67], v[180:181] op_sel_hi:[1,0]
	v_pk_mul_f32 v[72:73], v[64:65], v[180:181] op_sel_hi:[1,0]
	v_pk_mul_f32 v[62:63], v[62:63], v[180:181] op_sel_hi:[1,0]
	v_pk_mul_f32 v[60:61], v[60:61], v[180:181] op_sel_hi:[1,0]
	v_add_f32_e32 v64, 0, v32
	v_mov_b32_e32 v181, v142
	global_load_dwordx4 v[40:43], v[128:129], off offset:1024
	global_load_dwordx4 v[36:39], v[128:129], off offset:1088
	global_load_dwordx4 v[32:35], v[130:131], off offset:1024
	s_nop 0
	global_load_dwordx4 v[128:131], v[130:131], off offset:1088
	s_nop 0
	global_load_dwordx4 v[132:135], v[136:137], off offset:1024
	global_load_dwordx4 v[140:143], v[136:137], off offset:1088
	s_nop 0
	global_load_dwordx4 v[136:139], v[184:185], off offset:1088
	global_load_dwordx4 v[20:23], v[184:185], off offset:1024
	s_waitcnt lgkmcnt(2)
	v_mov_b32_e32 v184, v195
	v_add_f32_e32 v66, v187, v191
	v_add_f32_e32 v185, v186, v190
	v_add_f32_e32 v67, v189, v249
	v_add_f32_e32 v186, v188, v204
	v_cndmask_b32_e64 v185, v235, v185, s[44:45]
	v_cndmask_b32_e64 v66, v235, v66, s[20:21]
	v_add_f32_e32 v187, v218, v206
	v_add_f32_e32 v189, v219, v207
	v_add_f32_e32 v190, v220, v230
	v_add_f32_e32 v191, v221, v231
	v_cndmask_b32_e64 v186, v235, v186, s[22:23]
	v_cndmask_b32_e64 v67, v235, v67, s[24:25]
	v_mfma_f32_16x16x32_bf16 v[218:221], v[56:59], v[238:241], v[242:245]
	v_max3_f32 v58, v185, s98, v66
	s_waitcnt lgkmcnt(0)
	v_mov_b32_e32 v188, v203
	v_add_f32_e32 v203, v222, v246
	v_add_f32_e32 v204, v223, v217
	v_add_f32_e32 v206, v224, v250
	v_add_f32_e32 v207, v225, v237
	v_cndmask_b32_e64 v187, v235, v187, s[46:47]
	v_cndmask_b32_e64 v189, v235, v189, s[28:29]
	v_mfma_f32_16x16x32_bf16 v[222:225], v[52:55], v[238:241], v[80:83]
	v_max3_f32 v52, v58, v186, v67
	v_cndmask_b32_e64 v190, v235, v190, s[30:31]
	v_cndmask_b32_e64 v191, v235, v191, s[34:35]
	v_max3_f32 v52, v52, v187, v189
	v_cndmask_b32_e64 v203, v235, v203, s[48:49]
	v_cndmask_b32_e64 v204, v235, v204, s[38:39]
	v_max3_f32 v52, v52, v190, v191
	v_cndmask_b32_e64 v56, v235, v206, s[40:41]
	v_cndmask_b32_e64 v57, v235, v207, s[42:43]
	v_max3_f32 v52, v52, v203, v204
	v_max3_f32 v52, v52, v56, v57
	v_mov_b32_e32 v53, v52
	s_nop 1
	v_permlane16_swap_b32_e32 v52, v53
	v_max_f32_e32 v53, v53, v53
	v_max_f32_e32 v52, v52, v52
	v_max_f32_e32 v52, v52, v53
	v_mov_b32_e32 v53, v52
	s_nop 1
	v_permlane32_swap_b32_e32 v52, v53
	v_max3_f32 v207, v216, v52, v53
	v_sub_f32_e32 v52, v216, v207
	v_sub_f32_e32 v82, v204, v207
	v_exp_f32_e32 v204, v52
	v_mov_b32_e32 v195, v201
	v_mov_b32_e32 v201, v252
	v_sub_f32_e32 v53, v185, v207
	v_sub_f32_e32 v54, v66, v207
	v_sub_f32_e32 v55, v186, v207
	v_sub_f32_e32 v58, v67, v207
	v_sub_f32_e32 v59, v187, v207
	v_sub_f32_e32 v66, v189, v207
	v_sub_f32_e32 v67, v190, v207
	v_sub_f32_e32 v80, v191, v207
	v_sub_f32_e32 v81, v203, v207
	v_sub_f32_e32 v56, v56, v207
	v_sub_f32_e32 v57, v57, v207
	v_add_f32_e32 v165, v247, v64
	v_cvt_pk_bf16_f32 v64, v193, v193
	v_cvt_pk_bf16_f32 v65, v193, v193
	v_exp_f32_e32 v203, v53
	v_exp_f32_e32 v237, v54
	v_exp_f32_e32 v246, v55
	v_exp_f32_e32 v247, v58
	v_exp_f32_e32 v191, v59
	v_exp_f32_e32 v189, v66
	v_exp_f32_e32 v187, v67
	v_exp_f32_e32 v83, v80
	v_exp_f32_e32 v81, v81
	v_exp_f32_e32 v185, v82
	v_exp_f32_e32 v59, v56
	v_exp_f32_e32 v57, v57
	v_pk_mul_f32 v[226:227], v[44:45], v[204:205] op_sel_hi:[1,0]
	v_cvt_pk_bf16_f32 v66, v203, v237
	v_cvt_pk_bf16_f32 v67, v246, v247
	v_cvt_pk_bf16_f32 v52, v191, v189
	v_cvt_pk_bf16_f32 v53, v187, v83
	v_cvt_pk_bf16_f32 v54, v81, v185
	v_cvt_pk_bf16_f32 v55, v59, v57
	v_pk_mul_f32 v[228:229], v[46:47], v[204:205] op_sel_hi:[1,0]
; __device__ __forceinline__ v4i16_t vtr(LAS unsigned char* p) { return __builtin_amdgcn_ds_read_tr16_b64_v4i16((LAS v4i16_t*)p); }
; __device__ __forceinline__ void mixer_attn(const bf16_t* Z, bf16_t* MIX, int b, int r, LAS unsigned char* lds) {
;     ...
;         sm<2>(sA, bA, m0[2], mrun[2], lrun[2], o[2], pf[3], pf[4]);
;         sm<3>(sB, bB, m0[3], mrun[3], lrun[3], o[3], dummy, pf[5]);
; #pragma unroll
;         for (int dt = 0; dt < 4; ++dt) {
;             const bf16x8 a01 = cat8(vtr(vrd + 32 * dt), vtr(vrd + 16 * VS + 32 * dt)), a23 = cat8(vtr(vrd + 32 * VS + 32 * dt), vtr(vrd + 48 * VS + 32 * dt));
;             o[0][dt] = __builtin_amdgcn_mfma_f32_16x16x32_bf16(a01, pf[0], o[0][dt], 0, 0, 0);
;             o[1][dt] = __builtin_amdgcn_mfma_f32_16x16x32_bf16(a01, pf[1], o[1][dt], 0, 0, 0);
;             o[1][dt] = __builtin_amdgcn_mfma_f32_16x16x32_bf16(a23, pf[2], o[1][dt], 0, 0, 0);
;             o[2][dt] = __builtin_amdgcn_mfma_f32_16x16x32_bf16(a01, pf[3], o[2][dt], 0, 0, 0);
;             o[2][dt] = __builtin_amdgcn_mfma_f32_16x16x32_bf16(a23, pf[4], o[2][dt], 0, 0, 0);
;             o[3][dt] = __builtin_amdgcn_mfma_f32_16x16x32_bf16(a23, pf[5], o[3][dt], 0, 0, 0);
;         }
	v_add_f32_e32 v44, v218, v201
	v_add_f32_e32 v45, v219, v253
	v_add_f32_e32 v46, v220, v194
	v_add_f32_e32 v47, v221, v184
	v_cndmask_b32_e64 v44, v235, v44, s[50:51]
	v_cndmask_b32_e64 v45, v235, v45, s[52:53]
	v_add_f32_e32 v56, v222, v200
	v_add_f32_e32 v58, v223, v195
	v_cndmask_b32_e64 v46, v235, v46, s[54:55]
	v_cndmask_b32_e64 v47, v235, v47, s[56:57]
	v_max3_f32 v184, v44, s98, v45
	v_add_f32_e32 v80, v224, v202
	v_add_f32_e32 v82, v225, v188
	v_cndmask_b32_e64 v56, v235, v56, s[58:59]
	v_cndmask_b32_e64 v58, v235, v58, s[60:61]
	v_max3_f32 v184, v184, v46, v47
	v_cndmask_b32_e64 v80, v235, v80, s[62:63]
	v_cndmask_b32_e64 v82, v235, v82, s[64:65]
	v_max3_f32 v184, v184, v56, v58
	v_max3_f32 v184, v184, v80, v82
	v_mov_b32_e32 v186, v184
	s_nop 1
	v_permlane16_swap_b32_e32 v184, v186
	v_max_f32_e32 v186, v186, v186
	v_max_f32_e32 v184, v184, v184
	v_max_f32_e32 v184, v184, v186
	v_mov_b32_e32 v186, v184
	s_nop 1
	v_permlane32_swap_b32_e32 v184, v186
	v_max3_f32 v194, v192, v184, v186
	v_sub_f32_e32 v44, v44, v194
	v_sub_f32_e32 v45, v45, v194
	v_sub_f32_e32 v46, v46, v194
	v_sub_f32_e32 v47, v47, v194
	v_sub_f32_e32 v56, v56, v194
	v_sub_f32_e32 v58, v58, v194
	v_sub_f32_e32 v195, v80, v194
	v_sub_f32_e32 v200, v82, v194
	v_exp_f32_e32 v190, v44
	v_exp_f32_e32 v188, v45
	v_exp_f32_e32 v186, v46
	v_exp_f32_e32 v82, v47
	v_exp_f32_e32 v80, v56
	v_exp_f32_e32 v184, v58
	v_exp_f32_e32 v58, v195
	v_exp_f32_e32 v56, v200
	v_cvt_pk_bf16_f32 v44, v190, v188
	v_cvt_pk_bf16_f32 v45, v186, v82
	v_cvt_pk_bf16_f32 v46, v80, v184
	v_cvt_pk_bf16_f32 v47, v58, v56
	ds_read_b64_tr_b16 v[218:219], v213 offset:2304
	ds_read_b64_tr_b16 v[216:217], v213
	s_waitcnt lgkmcnt(0)
	v_mfma_f32_16x16x32_bf16 v[48:51], v[216:219], v[144:147], v[48:51]
	ds_read_b64_tr_b16 v[220:221], v213 offset:4608
	ds_read_b64_tr_b16 v[222:223], v213 offset:6912
	ds_read_b64_tr_b16 v[224:225], v213 offset:32
	v_mfma_f32_16x16x32_bf16 v[152:155], v[216:219], v[84:87], v[152:155]
	v_mul_f32_e64 v30, v30, v204
	v_mul_f32_e64 v31, v31, v204
	v_pk_mul_f32 v[28:29], v[28:29], v[204:205] op_sel_hi:[1,0]
	ds_read_b64_tr_b16 v[230:231], v213 offset:6944
	v_mfma_f32_16x16x32_bf16 v[216:219], v[216:219], v[64:67], v[226:229]
	ds_read_b64_tr_b16 v[238:239], v213 offset:4672
	ds_read_b64_tr_b16 v[240:241], v213 offset:6976
	v_sub_f32_e32 v192, v192, v194
	ds_read_b64_tr_b16 v[226:227], v213 offset:2336
	s_waitcnt lgkmcnt(0)
	v_mfma_f32_16x16x32_bf16 v[68:71], v[224:227], v[144:147], v[68:71]
	ds_read_b64_tr_b16 v[228:229], v213 offset:4640
	v_exp_f32_e32 v206, v192
	v_pk_mul_f32 v[26:27], v[26:27], v[204:205] op_sel_hi:[1,0]
	v_mfma_f32_16x16x32_bf16 v[148:151], v[224:227], v[84:87], v[148:151]
	v_mul_f32_e64 v24, v24, v204
	v_mul_f32_e64 v25, v25, v204
	v_pk_mul_f32 v[14:15], v[14:15], v[206:207] op_sel_hi:[1,0]
	v_pk_mul_f32 v[12:13], v[12:13], v[206:207] op_sel_hi:[1,0]
	v_mfma_f32_16x16x32_bf16 v[28:31], v[224:227], v[64:67], v[28:31]
	ds_read_b64_tr_b16 v[224:225], v213 offset:64
	ds_read_b64_tr_b16 v[226:227], v213 offset:2368
	v_pk_mul_f32 v[10:11], v[10:11], v[206:207] op_sel_hi:[1,0]
	s_waitcnt lgkmcnt(0)
	v_mfma_f32_16x16x32_bf16 v[242:245], v[224:227], v[84:87], v[72:75]
	s_nop 2
	ds_read_b64_tr_b16 v[72:73], v213 offset:96
	ds_read_b64_tr_b16 v[74:75], v213 offset:2400
	v_pk_mul_f32 v[8:9], v[8:9], v[206:207] op_sel_hi:[1,0]
	v_mfma_f32_16x16x32_bf16 v[76:79], v[224:227], v[144:147], v[76:79]
	v_mul_f32_e64 v6, v6, v206
	v_mul_f32_e64 v7, v7, v206
	v_pk_mul_f32 v[4:5], v[4:5], v[206:207] op_sel_hi:[1,0]
	v_pk_mul_f32 v[2:3], v[2:3], v[206:207] op_sel_hi:[1,0]
	s_waitcnt lgkmcnt(0)
	v_mfma_f32_16x16x32_bf16 v[88:91], v[72:75], v[144:147], v[88:91]
	v_add_f32_e32 v144, v248, v165
	v_add_f32_e32 v192, v251, v144
	ds_read_b64_tr_b16 v[144:145], v213 offset:4704
	ds_read_b64_tr_b16 v[146:147], v213 offset:7008
	v_pk_add_f32 v[182:183], v[182:183], v[192:193]
	v_pk_mul_f32 v[0:1], v[0:1], v[206:207] op_sel_hi:[1,0]
	v_mfma_f32_16x16x32_bf16 v[12:15], v[220:223], v[44:47], v[12:15]
	v_mul_f32_e64 v18, v18, v204
	v_mul_f32_e64 v19, v19, v204
	v_pk_mul_f32 v[16:17], v[16:17], v[204:205] op_sel_hi:[1,0]
	v_mov_b32_e32 v164, v193
	v_mfma_f32_16x16x32_bf16 v[8:11], v[228:231], v[44:47], v[8:11]
	s_mov_b32 s33, s84
	s_cmp_eq_u32 s84, 8
	v_mov_b32_e32 v192, v194
	v_mfma_f32_16x16x32_bf16 v[4:7], v[238:241], v[44:47], v[4:7]
	s_waitcnt lgkmcnt(0)
	v_mfma_f32_16x16x32_bf16 v[0:3], v[144:147], v[44:47], v[0:3]
	v_add_f32_e64 v44, v178, v182
	v_add_f32_e64 v45, v179, v183
	v_pk_add_f32 v[44:45], v[176:177], v[44:45]
	v_mfma_f32_16x16x32_bf16 v[24:27], v[224:227], v[64:67], v[24:27]
	v_add_f32_e64 v44, v174, v44
	v_add_f32_e64 v45, v175, v45
	v_pk_add_f32 v[44:45], v[168:169], v[44:45]
	v_mfma_f32_16x16x32_bf16 v[16:19], v[72:75], v[64:67], v[16:19]
	v_add_f32_e64 v44, v172, v44
	v_add_f32_e64 v45, v173, v45
	v_pk_add_f32 v[64:65], v[170:171], v[44:45]
	v_mfma_f32_16x16x32_bf16 v[60:63], v[72:75], v[84:87], v[60:63]
	v_add_f32_e64 v64, v166, v64
	v_add_f32_e64 v65, v167, v65
	v_pk_fma_f32 v[162:163], v[162:163], v[180:181], v[64:65]
	v_add_f32_e32 v64, 0, v203
	v_add_f32_e32 v64, v237, v64
	v_add_f32_e32 v64, v246, v64
	v_add_f32_e32 v165, v247, v64
	v_mfma_f32_16x16x32_bf16 v[72:75], v[228:231], v[92:95], v[148:151]
	s_nop 2
	v_add_f32_e64 v148, v190, v164
	v_add_f32_e64 v149, v191, v165
	v_mfma_f32_16x16x32_bf16 v[84:87], v[220:223], v[92:95], v[152:155]
	v_add_f32_e64 v148, v188, v148
	v_add_f32_e64 v149, v189, v149
	v_pk_add_f32 v[148:149], v[186:187], v[148:149]
	v_mfma_f32_16x16x32_bf16 v[44:47], v[220:223], v[52:55], v[216:219]
	v_add_f32_e64 v82, v82, v148
	v_add_f32_e64 v83, v83, v149
	v_pk_add_f32 v[80:81], v[80:81], v[82:83]
	v_mfma_f32_16x16x32_bf16 v[28:31], v[228:231], v[52:55], v[28:31]
	v_add_f32_e64 v80, v184, v80
	v_add_f32_e64 v81, v185, v81
	v_mov_b32_e32 v216, v207
	v_pk_add_f32 v[58:59], v[58:59], v[80:81]
	v_mfma_f32_16x16x32_bf16 v[64:67], v[238:241], v[92:95], v[242:245]
	v_mov_b32_e32 v207, v204
	v_pk_add_f32 v[56:57], v[56:57], v[58:59]
	s_waitcnt vmcnt(3)
	v_mov_b64_e32 v[80:81], v[132:133]
	v_mfma_f32_16x16x32_bf16 v[24:27], v[238:241], v[52:55], v[24:27]
	v_fma_f32 v158, v158, v206, v56
	v_fma_f32 v159, v159, v207, v57
	s_waitcnt vmcnt(1)
	v_mov_b64_e32 v[56:57], v[136:137]
	v_mov_b64_e32 v[82:83], v[134:135]
	v_mfma_f32_16x16x32_bf16 v[60:63], v[144:147], v[92:95], v[60:63]
	v_mov_b64_e32 v[92:93], v[128:129]
	v_mov_b64_e32 v[94:95], v[130:131]
	v_mov_b64_e32 v[58:59], v[138:139]
	v_mfma_f32_16x16x32_bf16 v[16:19], v[144:147], v[52:55], v[16:19]
	v_mov_b64_e32 v[52:53], v[140:141]
	v_mov_b64_e32 v[54:55], v[142:143]
	s_cbranch_scc0 .LBB0_289
; __device__ __forceinline__ void mixer_attn(const bf16_t* Z, bf16_t* MIX, int b, int r, LAS unsigned char* lds) {
;     ...
; #pragma unroll
;     for (int jq = 0; jq < 4; ++jq) {
;         const float lt = xrow16_sum(lrun[jq]);
;         const float inv = 1.0f / lt; float ss = 0.f;
; #pragma unroll
;         for (int dt = 0; dt < 4; ++dt) { o[jq][dt] *= inv; ss += (o[jq][dt][0] * o[jq][dt][0] + o[jq][dt][1] * o[jq][dt][1]) + (o[jq][dt][2] * o[jq][dt][2] + o[jq][dt][3] * o[jq][dt][3]); }
;         ss = xrow16_sum(ss);
;         if (g == 0) ssbuf[h * 64 + 16 * jq + i] = ss;
;     }
	s_waitcnt vmcnt(0)
	v_mov_b32_e32 v20, v163
	s_nop 1
	v_permlane16_swap_b32_e32 v163, v20
	v_add_f32_e32 v20, v163, v20
	s_lshl_b32 s0, s0, 2
	v_mov_b32_e32 v21, v20
	s_add_i32 s0, s0, 0
	s_nop 0
	v_permlane32_swap_b32_e32 v20, v21
	s_add_i32 s0, s0, 0x26800
	v_add_f32_e32 v20, v20, v21
	v_lshl_add_u32 v80, v205, 2, s0
	v_div_scale_f32 v21, s[0:1], v20, v20, 1.0
	v_rcp_f32_e32 v22, v21
	v_cmp_gt_u32_e64 s[4:5], 16, v209
	v_fma_f32 v23, -v21, v22, 1.0
	v_fmac_f32_e32 v22, v23, v22
	v_div_scale_f32 v23, vcc, 1.0, v20, 1.0
	v_mul_f32_e32 v32, v23, v22
	v_fma_f32 v33, -v21, v32, v23
	v_fmac_f32_e32 v32, v33, v22
	v_fma_f32 v21, -v21, v32, v23
	v_div_fmas_f32 v21, v21, v22, v32
	v_div_fixup_f32 v22, v21, v20, 1.0
	v_pk_mul_f32 v[40:41], v[50:51], v[22:23] op_sel_hi:[1,0]
	v_pk_mul_f32 v[42:43], v[48:49], v[22:23] op_sel_hi:[1,0]
	v_mul_f32_e32 v21, v41, v41
	v_mul_f32_e32 v20, v43, v43
	v_fmac_f32_e32 v20, v42, v42
	v_fmac_f32_e32 v21, v40, v40
	v_pk_mul_f32 v[36:37], v[70:71], v[22:23] op_sel_hi:[1,0]
	v_pk_mul_f32 v[38:39], v[68:69], v[22:23] op_sel_hi:[1,0]
	v_add_f32_e32 v20, v20, v21
	v_mul_f32_e32 v21, v39, v39
	v_mul_f32_e32 v23, v37, v37
	v_fmac_f32_e32 v21, v38, v38
	v_fmac_f32_e32 v23, v36, v36
	v_add_f32_e32 v21, v21, v23
	v_pk_mul_f32 v[32:33], v[78:79], v[22:23] op_sel_hi:[1,0]
	v_pk_mul_f32 v[34:35], v[76:77], v[22:23] op_sel_hi:[1,0]
	v_add_f32_e32 v20, v20, v21
	v_mul_f32_e32 v21, v35, v35
	v_mul_f32_e32 v23, v33, v33
	v_fmac_f32_e32 v21, v34, v34
	v_fmac_f32_e32 v23, v32, v32
	v_add_f32_e32 v21, v21, v23
	v_add_f32_e32 v48, v21, v20
	v_pk_mul_f32 v[20:21], v[90:91], v[22:23] op_sel_hi:[1,0]
	v_pk_mul_f32 v[22:23], v[88:89], v[22:23] op_sel_hi:[1,0]
	v_mul_f32_e32 v50, v21, v21
	v_mul_f32_e32 v49, v23, v23
	v_fmac_f32_e32 v49, v22, v22
	v_fmac_f32_e32 v50, v20, v20
	v_add_f32_e32 v49, v49, v50
	v_add_f32_e32 v48, v49, v48
	v_mov_b32_e32 v49, v48
	s_nop 1
	v_permlane16_swap_b32_e32 v48, v49
	v_add_f32_e32 v48, v48, v49
	v_mov_b32_e32 v49, v48
	s_nop 1
	v_permlane32_swap_b32_e32 v48, v49
	s_and_saveexec_b64 s[0:1], s[4:5]
	v_add_f32_e32 v48, v48, v49
	ds_write_b32 v80, v48
	s_or_b64 exec, exec, s[0:1]
	v_mov_b32_e32 v48, v162
	s_nop 1
	v_permlane16_swap_b32_e32 v162, v48
	v_add_f32_e32 v48, v162, v48
	v_mov_b32_e32 v49, v48
	s_nop 1
	v_permlane32_swap_b32_e32 v48, v49
	v_add_f32_e32 v48, v48, v49
	v_div_scale_f32 v49, s[0:1], v48, v48, 1.0
	v_rcp_f32_e32 v50, v49
	s_nop 0
	v_fma_f32 v51, -v49, v50, 1.0
	v_fmac_f32_e32 v50, v51, v50
	v_div_scale_f32 v51, vcc, 1.0, v48, 1.0
	v_mul_f32_e32 v52, v51, v50
	v_fma_f32 v53, -v49, v52, v51
	v_fmac_f32_e32 v52, v53, v50
	v_fma_f32 v49, -v49, v52, v51
	v_div_fmas_f32 v49, v49, v50, v52
	v_div_fixup_f32 v50, v49, v48, 1.0
	v_pk_mul_f32 v[68:69], v[86:87], v[50:51] op_sel_hi:[1,0]
	v_pk_mul_f32 v[70:71], v[84:85], v[50:51] op_sel_hi:[1,0]
	v_mul_f32_e32 v49, v69, v69
	v_mul_f32_e32 v48, v71, v71
	v_fmac_f32_e32 v48, v70, v70
	v_fmac_f32_e32 v49, v68, v68
	v_pk_mul_f32 v[56:57], v[74:75], v[50:51] op_sel_hi:[1,0]
	v_pk_mul_f32 v[58:59], v[72:73], v[50:51] op_sel_hi:[1,0]
	v_add_f32_e32 v48, v48, v49
	v_mul_f32_e32 v49, v59, v59
	v_mul_f32_e32 v51, v57, v57
	v_fmac_f32_e32 v49, v58, v58
	v_fmac_f32_e32 v51, v56, v56
	v_add_f32_e32 v49, v49, v51
	v_pk_mul_f32 v[52:53], v[66:67], v[50:51] op_sel_hi:[1,0]
	v_pk_mul_f32 v[54:55], v[64:65], v[50:51] op_sel_hi:[1,0]
	v_add_f32_e32 v48, v48, v49
	v_mul_f32_e32 v49, v55, v55
	v_mul_f32_e32 v51, v53, v53
	v_fmac_f32_e32 v49, v54, v54
	v_fmac_f32_e32 v51, v52, v52
	v_add_f32_e32 v49, v49, v51
	v_add_f32_e32 v64, v49, v48
	v_pk_mul_f32 v[48:49], v[62:63], v[50:51] op_sel_hi:[1,0]
	v_pk_mul_f32 v[50:51], v[60:61], v[50:51] op_sel_hi:[1,0]
	v_mul_f32_e32 v61, v49, v49
	v_mul_f32_e32 v60, v51, v51
	v_fmac_f32_e32 v60, v50, v50
	v_fmac_f32_e32 v61, v48, v48
	v_add_f32_e32 v60, v60, v61
	v_add_f32_e32 v60, v60, v64
	v_mov_b32_e32 v61, v60
	s_nop 1
	v_permlane16_swap_b32_e32 v60, v61
	v_add_f32_e32 v60, v60, v61
	v_mov_b32_e32 v61, v60
	s_nop 1
	v_permlane32_swap_b32_e32 v60, v61
	s_and_saveexec_b64 s[0:1], s[4:5]
	v_readlane_b32 s74, v255, 9
	v_readlane_b32 s75, v255, 10
	v_add_f32_e32 v60, v60, v61
	ds_write_b32 v80, v60 offset:64
	s_or_b64 exec, exec, s[0:1]
	v_mov_b32_e32 v60, v159
	s_nop 1
	v_permlane16_swap_b32_e32 v159, v60
	v_add_f32_e32 v60, v159, v60
	v_mov_b32_e32 v61, v60
	s_nop 1
	v_permlane32_swap_b32_e32 v60, v61
	v_add_f32_e32 v60, v60, v61
	v_div_scale_f32 v61, s[0:1], v60, v60, 1.0
	v_rcp_f32_e32 v62, v61
	s_nop 0
	v_fma_f32 v63, -v61, v62, 1.0
	v_fmac_f32_e32 v62, v63, v62
	v_div_scale_f32 v63, vcc, 1.0, v60, 1.0
	v_mul_f32_e32 v64, v63, v62
	v_fma_f32 v65, -v61, v64, v63
	v_fmac_f32_e32 v64, v65, v62
	v_fma_f32 v61, -v61, v64, v63
	v_div_fmas_f32 v61, v61, v62, v64
	v_div_fixup_f32 v60, v61, v60, 1.0
	v_pk_mul_f32 v[46:47], v[46:47], v[60:61] op_sel_hi:[1,0]
	v_pk_mul_f32 v[44:45], v[44:45], v[60:61] op_sel_hi:[1,0]
	v_mul_f32_e32 v62, v47, v47
	v_mul_f32_e32 v61, v45, v45
	v_fmac_f32_e32 v61, v44, v44
	v_fmac_f32_e32 v62, v46, v46
	v_add_f32_e32 v61, v61, v62
	v_pk_mul_f32 v[30:31], v[30:31], v[60:61] op_sel_hi:[1,0]
	v_pk_mul_f32 v[28:29], v[28:29], v[60:61] op_sel_hi:[1,0]
	v_mul_f32_e32 v63, v31, v31
	v_mul_f32_e32 v62, v29, v29
	v_fmac_f32_e32 v62, v28, v28
	v_fmac_f32_e32 v63, v30, v30
	v_add_f32_e32 v62, v62, v63
	v_add_f32_e32 v61, v61, v62
	v_pk_mul_f32 v[26:27], v[26:27], v[60:61] op_sel_hi:[1,0]
	v_pk_mul_f32 v[24:25], v[24:25], v[60:61] op_sel_hi:[1,0]
	v_mul_f32_e32 v63, v27, v27
	v_mul_f32_e32 v62, v25, v25
	v_fmac_f32_e32 v62, v24, v24
	v_fmac_f32_e32 v63, v26, v26
	v_add_f32_e32 v62, v62, v63
	v_add_f32_e32 v61, v62, v61
; __device__ __forceinline__ unsigned cvt_pk_bf16(float lo, float hi) { unsigned r; asm volatile("v_cvt_pk_bf16_f32 %0, %1, %2" : "=v"(r) : "v"(lo), "v"(hi)); return r; }
; __device__ __forceinline__ void mixer_attn(const bf16_t* Z, bf16_t* MIX, int b, int r, LAS unsigned char* lds) {
;     ...
; #pragma unroll
;     for (int jq = 0; jq < 4; ++jq) {
;         const float lt = xrow16_sum(lrun[jq]);
;         const float inv = 1.0f / lt; float ss = 0.f;
; #pragma unroll
;         for (int dt = 0; dt < 4; ++dt) { o[jq][dt] *= inv; ss += (o[jq][dt][0] * o[jq][dt][0] + o[jq][dt][1] * o[jq][dt][1]) + (o[jq][dt][2] * o[jq][dt][2] + o[jq][dt][3] * o[jq][dt][3]); }
;         ss = xrow16_sum(ss);
;         if (g == 0) ssbuf[h * 64 + 16 * jq + i] = ss;
;     }
;     __syncthreads();
;     bf16_t* mo = MIX + ((size_t)b * SEQ + r * 64) * DM + h * 64 + 4 * g;
; #pragma unroll
;     for (int jq = 0; jq < 4; ++jq) {
;         float tot = 0.f;
; #pragma unroll
;         for (int hh = 0; hh < 8; ++hh) tot += ssbuf[hh * 64 + 16 * jq + i];
;         const float rinv = __builtin_amdgcn_rsqf(tot * (1.0f / 512.0f) + EPS);
; #pragma unroll
;         for (int dt = 0; dt < 4; ++dt) { const f32x4 v = o[jq][dt] * rinv;
;             *(unsigned long long*)(mo + (size_t)(16 * jq + i) * DM + 16 * dt) = (unsigned long long)pg8::cvt_pk_bf16(v[0], v[1]) | ((unsigned long long)pg8::cvt_pk_bf16(v[2], v[3]) << 32); }
	v_pk_mul_f32 v[18:19], v[18:19], v[60:61] op_sel_hi:[1,0]
	v_pk_mul_f32 v[16:17], v[16:17], v[60:61] op_sel_hi:[1,0]
	v_mul_f32_e32 v62, v19, v19
	v_mul_f32_e32 v60, v17, v17
	v_fmac_f32_e32 v60, v16, v16
	v_fmac_f32_e32 v62, v18, v18
	v_add_f32_e32 v60, v60, v62
	v_add_f32_e32 v60, v60, v61
	v_mov_b32_e32 v61, v60
	s_nop 1
	v_permlane16_swap_b32_e32 v60, v61
	v_add_f32_e32 v60, v60, v61
	v_mov_b32_e32 v61, v60
	s_nop 1
	v_permlane32_swap_b32_e32 v60, v61
	s_and_saveexec_b64 s[0:1], s[4:5]
	v_readlane_b32 s72, v255, 7
	v_readlane_b32 s73, v255, 8
	v_add_f32_e32 v60, v60, v61
	ds_write_b32 v80, v60 offset:128
	s_or_b64 exec, exec, s[0:1]
	v_mov_b32_e32 v60, v158
	s_nop 1
	v_permlane16_swap_b32_e32 v158, v60
	v_add_f32_e32 v60, v158, v60
	v_mov_b32_e32 v61, v60
	s_nop 1
	v_permlane32_swap_b32_e32 v60, v61
	v_add_f32_e32 v60, v60, v61
	v_div_scale_f32 v61, s[0:1], v60, v60, 1.0
	v_rcp_f32_e32 v62, v61
	s_nop 0
	v_fma_f32 v63, -v61, v62, 1.0
	v_fmac_f32_e32 v62, v63, v62
	v_div_scale_f32 v63, vcc, 1.0, v60, 1.0
	v_mul_f32_e32 v64, v63, v62
	v_fma_f32 v65, -v61, v64, v63
	v_fmac_f32_e32 v64, v65, v62
	v_fma_f32 v61, -v61, v64, v63
	v_div_fmas_f32 v61, v61, v62, v64
	v_div_fixup_f32 v60, v61, v60, 1.0
	v_pk_mul_f32 v[14:15], v[14:15], v[60:61] op_sel_hi:[1,0]
	v_pk_mul_f32 v[12:13], v[12:13], v[60:61] op_sel_hi:[1,0]
	v_mul_f32_e32 v62, v15, v15
	v_mul_f32_e32 v61, v13, v13
	v_fmac_f32_e32 v61, v12, v12
	v_fmac_f32_e32 v62, v14, v14
	v_add_f32_e32 v61, v61, v62
	v_pk_mul_f32 v[10:11], v[10:11], v[60:61] op_sel_hi:[1,0]
	v_pk_mul_f32 v[8:9], v[8:9], v[60:61] op_sel_hi:[1,0]
	v_mul_f32_e32 v63, v11, v11
	v_mul_f32_e32 v62, v9, v9
	v_fmac_f32_e32 v62, v8, v8
	v_fmac_f32_e32 v63, v10, v10
	v_add_f32_e32 v62, v62, v63
	v_add_f32_e32 v61, v61, v62
	v_pk_mul_f32 v[6:7], v[6:7], v[60:61] op_sel_hi:[1,0]
	v_pk_mul_f32 v[4:5], v[4:5], v[60:61] op_sel_hi:[1,0]
	v_mul_f32_e32 v63, v7, v7
	v_mul_f32_e32 v62, v5, v5
	v_fmac_f32_e32 v62, v4, v4
	v_fmac_f32_e32 v63, v6, v6
	v_add_f32_e32 v62, v62, v63
	v_add_f32_e32 v61, v62, v61
	v_pk_mul_f32 v[2:3], v[2:3], v[60:61] op_sel_hi:[1,0]
	v_pk_mul_f32 v[0:1], v[0:1], v[60:61] op_sel_hi:[1,0]
	v_mul_f32_e32 v62, v3, v3
	v_mul_f32_e32 v60, v1, v1
	v_fmac_f32_e32 v60, v0, v0
	v_fmac_f32_e32 v62, v2, v2
	v_add_f32_e32 v60, v60, v62
	v_add_f32_e32 v60, v60, v61
	v_mov_b32_e32 v61, v60
	s_nop 1
	v_permlane16_swap_b32_e32 v60, v61
	v_add_f32_e32 v60, v60, v61
	v_mov_b32_e32 v61, v60
	s_nop 1
	v_permlane32_swap_b32_e32 v60, v61
	s_and_saveexec_b64 s[0:1], s[4:5]
	v_readlane_b32 s76, v255, 19
	v_add_f32_e32 v60, v60, v61
	ds_write_b32 v80, v60 offset:192
	s_or_b64 exec, exec, s[0:1]
	v_lshl_add_u32 v60, v205, 2, 0
	v_add_u32_e32 v72, 0x26800, v60
	s_waitcnt lgkmcnt(0)
	s_barrier
	ds_read2st64_b32 v[60:61], v72 offset1:1
	ds_read2st64_b32 v[62:63], v72 offset0:2 offset1:3
	ds_read2st64_b32 v[64:65], v72 offset0:4 offset1:5
	ds_read2st64_b32 v[66:67], v72 offset0:6 offset1:7
	s_lshl_b64 s[0:1], s[96:97], 11
	s_add_u32 s0, s74, s0
	s_addc_u32 s1, s75, s1
	s_waitcnt lgkmcnt(3)
	v_add_f32_e32 v60, 0, v60
	v_add_f32_e32 v60, v60, v61
	s_waitcnt lgkmcnt(2)
	v_add_f32_e32 v60, v60, v62
	v_add_f32_e32 v60, v60, v63
	s_waitcnt lgkmcnt(1)
	v_add_f32_e32 v60, v60, v64
	v_add_f32_e32 v60, v60, v65
	s_waitcnt lgkmcnt(0)
	v_add_f32_e32 v60, v60, v66
	v_add_f32_e32 v60, v60, v67
	v_fmamk_f32 v60, v60, 0x3b000000, v233
	v_rsq_f32_e32 v60, v60
	s_add_u32 s0, s0, s80
	s_addc_u32 s1, s1, s81
	v_lshlrev_b32_e32 v192, 1, v208
	v_lshl_add_u64 v[62:63], s[0:1], 0, v[192:193]
	v_lshlrev_b32_e32 v192, 11, v205
	v_lshl_add_u64 v[62:63], v[62:63], 0, v[192:193]
	v_pk_mul_f32 v[42:43], v[42:43], v[60:61] op_sel_hi:[1,0]
	v_pk_mul_f32 v[38:39], v[38:39], v[60:61] op_sel_hi:[1,0]
	v_pk_mul_f32 v[34:35], v[34:35], v[60:61] op_sel_hi:[1,0]
	v_pk_mul_f32 v[20:21], v[20:21], v[60:61] op_sel_hi:[1,0]
	v_pk_mul_f32 v[22:23], v[22:23], v[60:61] op_sel_hi:[1,0]
	v_pk_mul_f32 v[40:41], v[40:41], v[60:61] op_sel_hi:[1,0]
	v_cvt_pk_bf16_f32 v42, v42, v43
	v_pk_mul_f32 v[36:37], v[36:37], v[60:61] op_sel_hi:[1,0]
	v_cvt_pk_bf16_f32 v43, v40, v41
	global_store_dwordx2 v[62:63], v[42:43], off
	v_cvt_pk_bf16_f32 v38, v38, v39
	v_cvt_pk_bf16_f32 v39, v36, v37
	global_store_dwordx2 v[62:63], v[38:39], off offset:32
	v_pk_mul_f32 v[32:33], v[32:33], v[60:61] op_sel_hi:[1,0]
	v_cvt_pk_bf16_f32 v34, v34, v35
	v_add_u32_e32 v36, 64, v72
	v_cvt_pk_bf16_f32 v35, v32, v33
	global_store_dwordx2 v[62:63], v[34:35], off offset:64
	v_cvt_pk_bf16_f32 v22, v22, v23
	v_cvt_pk_bf16_f32 v23, v20, v21
	ds_read2_b32 v[20:21], v72 offset0:16 offset1:80
	ds_read2_b32 v[32:33], v72 offset0:144 offset1:208
	ds_read2st64_b32 v[34:35], v36 offset0:4 offset1:5
	global_store_dwordx2 v[62:63], v[22:23], off offset:96
	s_mov_b32 s0, 0x8000
	s_waitcnt lgkmcnt(2)
	v_add_f32_e32 v20, 0, v20
	v_add_f32_e32 v37, v20, v21
	ds_read2st64_b32 v[20:21], v36 offset0:6 offset1:7
	s_waitcnt lgkmcnt(2)
	v_add_f32_e32 v32, v37, v32
	v_add_f32_e32 v32, v32, v33
	s_waitcnt lgkmcnt(1)
	v_add_f32_e32 v32, v32, v34
	v_add_f32_e32 v32, v32, v35
	s_waitcnt lgkmcnt(0)
; __device__ __forceinline__ unsigned cvt_pk_bf16(float lo, float hi) { unsigned r; asm volatile("v_cvt_pk_bf16_f32 %0, %1, %2" : "=v"(r) : "v"(lo), "v"(hi)); return r; }
; __device__ __forceinline__ void mixer_attn(const bf16_t* Z, bf16_t* MIX, int b, int r, LAS unsigned char* lds) {
;     ...
; #pragma unroll
;     for (int jq = 0; jq < 4; ++jq) {
;         float tot = 0.f;
; #pragma unroll
;         for (int hh = 0; hh < 8; ++hh) tot += ssbuf[hh * 64 + 16 * jq + i];
;         const float rinv = __builtin_amdgcn_rsqf(tot * (1.0f / 512.0f) + EPS);
; #pragma unroll
;         for (int dt = 0; dt < 4; ++dt) { const f32x4 v = o[jq][dt] * rinv;
;             *(unsigned long long*)(mo + (size_t)(16 * jq + i) * DM + 16 * dt) = (unsigned long long)pg8::cvt_pk_bf16(v[0], v[1]) | ((unsigned long long)pg8::cvt_pk_bf16(v[2], v[3]) << 32); }
;     }
;     __syncthreads();
	v_add_f32_e32 v20, v32, v20
	v_add_f32_e32 v20, v20, v21
	v_fmamk_f32 v20, v20, 0x3b000000, v233
	v_rsq_f32_e32 v20, v20
	v_add_u32_e32 v38, 0x80, v72
	v_readlane_b32 s4, v255, 32
	v_readlane_b32 s5, v255, 33
	v_pk_mul_f32 v[22:23], v[68:69], v[20:21] op_sel_hi:[1,0]
	v_pk_mul_f32 v[32:33], v[70:71], v[20:21] op_sel_hi:[1,0]
	v_pk_mul_f32 v[34:35], v[58:59], v[20:21] op_sel_hi:[1,0]
	v_cvt_pk_bf16_f32 v32, v32, v33
	v_cvt_pk_bf16_f32 v33, v22, v23
	v_add_co_u32_e32 v22, vcc, s0, v62
	s_mov_b32 s0, 0x10000
	s_nop 0
	v_addc_co_u32_e32 v23, vcc, 0, v63, vcc
	global_store_dwordx2 v[22:23], v[32:33], off
	v_pk_mul_f32 v[32:33], v[56:57], v[20:21] op_sel_hi:[1,0]
	v_cvt_pk_bf16_f32 v34, v34, v35
	s_mov_b32 s2, 0
	v_cvt_pk_bf16_f32 v35, v32, v33
	global_store_dwordx2 v[22:23], v[34:35], off offset:32
	v_pk_mul_f32 v[32:33], v[52:53], v[20:21] op_sel_hi:[1,0]
	v_pk_mul_f32 v[34:35], v[54:55], v[20:21] op_sel_hi:[1,0]
	s_movk_i32 s10, 0x1000
	v_cvt_pk_bf16_f32 v34, v34, v35
	v_cvt_pk_bf16_f32 v35, v32, v33
	v_pk_mul_f32 v[32:33], v[48:49], v[20:21] op_sel_hi:[1,0]
	v_pk_mul_f32 v[20:21], v[50:51], v[20:21] op_sel_hi:[1,0]
	global_store_dwordx2 v[22:23], v[34:35], off offset:64
	v_cvt_pk_bf16_f32 v20, v20, v21
	v_cvt_pk_bf16_f32 v21, v32, v33
	ds_read2_b32 v[32:33], v72 offset0:32 offset1:96
	ds_read2_b32 v[34:35], v72 offset0:160 offset1:224
	ds_read2st64_b32 v[36:37], v38 offset0:4 offset1:5
	global_store_dwordx2 v[22:23], v[20:21], off offset:96
	s_waitcnt lgkmcnt(2)
	v_add_f32_e32 v32, 0, v32
	v_add_f32_e32 v39, v32, v33
	ds_read2st64_b32 v[32:33], v38 offset0:6 offset1:7
	s_waitcnt lgkmcnt(2)
	v_add_f32_e32 v34, v39, v34
	v_add_f32_e32 v34, v34, v35
	s_waitcnt lgkmcnt(1)
	v_add_f32_e32 v34, v34, v36
	v_add_f32_e32 v34, v34, v37
	s_waitcnt lgkmcnt(0)
	v_add_f32_e32 v32, v34, v32
	v_add_f32_e32 v32, v32, v33
	v_fmamk_f32 v32, v32, 0x3b000000, v233
	v_rsq_f32_e32 v32, v32
	s_nop 0
	v_pk_mul_f32 v[20:21], v[46:47], v[32:33] op_sel_hi:[1,0]
	v_pk_mul_f32 v[22:23], v[44:45], v[32:33] op_sel_hi:[1,0]
	v_pk_mul_f32 v[28:29], v[28:29], v[32:33] op_sel_hi:[1,0]
	v_cvt_pk_bf16_f32 v22, v22, v23
	v_cvt_pk_bf16_f32 v23, v20, v21
	v_add_co_u32_e32 v20, vcc, s0, v62
	v_pk_mul_f32 v[24:25], v[24:25], v[32:33] op_sel_hi:[1,0]
	s_nop 0
	v_addc_co_u32_e32 v21, vcc, 0, v63, vcc
	global_store_dwordx2 v[20:21], v[22:23], off
	v_pk_mul_f32 v[22:23], v[30:31], v[32:33] op_sel_hi:[1,0]
	v_pk_mul_f32 v[18:19], v[18:19], v[32:33] op_sel_hi:[1,0]
	v_pk_mul_f32 v[16:17], v[16:17], v[32:33] op_sel_hi:[1,0]
	v_cvt_pk_bf16_f32 v28, v28, v29
	v_cvt_pk_bf16_f32 v29, v22, v23
	global_store_dwordx2 v[20:21], v[28:29], off offset:32
	v_pk_mul_f32 v[22:23], v[26:27], v[32:33] op_sel_hi:[1,0]
	v_cvt_pk_bf16_f32 v24, v24, v25
	v_add_u32_e32 v26, 0xc0, v72
	v_cvt_pk_bf16_f32 v25, v22, v23
	global_store_dwordx2 v[20:21], v[24:25], off offset:64
	v_cvt_pk_bf16_f32 v16, v16, v17
	v_cvt_pk_bf16_f32 v17, v18, v19
	ds_read2_b32 v[18:19], v72 offset0:48 offset1:112
	ds_read2_b32 v[22:23], v72 offset0:176 offset1:240
	ds_read2st64_b32 v[24:25], v26 offset0:4 offset1:5
	global_store_dwordx2 v[20:21], v[16:17], off offset:96
	s_mov_b64 s[0:1], 0x1000
	s_waitcnt lgkmcnt(2)
	v_add_f32_e32 v18, 0, v18
	v_add_f32_e32 v27, v18, v19
	ds_read2st64_b32 v[18:19], v26 offset0:6 offset1:7
	s_waitcnt lgkmcnt(2)
	v_add_f32_e32 v22, v27, v22
	v_add_f32_e32 v22, v22, v23
	s_waitcnt lgkmcnt(1)
	v_add_f32_e32 v22, v22, v24
	v_add_f32_e32 v22, v22, v25
	s_waitcnt lgkmcnt(0)
	v_add_f32_e32 v18, v22, v18
	v_add_f32_e32 v18, v18, v19
	v_fmamk_f32 v18, v18, 0x3b000000, v233
	v_rsq_f32_e32 v18, v18
	v_mov_b32_e32 v24, v232
	v_pk_mul_f32 v[14:15], v[14:15], v[18:19] op_sel_hi:[1,0]
	v_pk_mul_f32 v[12:13], v[12:13], v[18:19] op_sel_hi:[1,0]
	v_pk_mul_f32 v[8:9], v[8:9], v[18:19] op_sel_hi:[1,0]
	v_cvt_pk_bf16_f32 v12, v12, v13
	v_cvt_pk_bf16_f32 v13, v14, v15
	v_add_co_u32_e32 v14, vcc, s3, v62
	v_pk_mul_f32 v[4:5], v[4:5], v[18:19] op_sel_hi:[1,0]
	s_nop 0
	v_addc_co_u32_e32 v15, vcc, 0, v63, vcc
	v_pk_mul_f32 v[0:1], v[0:1], v[18:19] op_sel_hi:[1,0]
	global_store_dwordx2 v[14:15], v[12:13], off
	v_pk_mul_f32 v[10:11], v[10:11], v[18:19] op_sel_hi:[1,0]
	v_cvt_pk_bf16_f32 v8, v8, v9
	v_pk_mul_f32 v[6:7], v[6:7], v[18:19] op_sel_hi:[1,0]
	v_cvt_pk_bf16_f32 v9, v10, v11
	global_store_dwordx2 v[14:15], v[8:9], off offset:32
	v_cvt_pk_bf16_f32 v4, v4, v5
	v_cvt_pk_bf16_f32 v5, v6, v7
	global_store_dwordx2 v[14:15], v[4:5], off offset:64
	v_cvt_pk_bf16_f32 v0, v0, v1
	v_pk_mul_f32 v[2:3], v[2:3], v[18:19] op_sel_hi:[1,0]
	s_nop 0
	v_cvt_pk_bf16_f32 v1, v2, v3
	global_store_dwordx2 v[14:15], v[0:1], off offset:96
	s_barrier
; __device__ __forceinline__ void unpack8(const u32x4 w, float* f) { f[0] = bf_lo(w.x); f[1] = bf_hi(w.x); f[2] = bf_lo(w.y); f[3] = bf_hi(w.y); f[4] = bf_lo(w.z); f[5] = bf_hi(w.z); f[6] = bf_lo(w.w); f[7] = bf_hi(w.w); }
; __device__ __forceinline__ void mixer_conv(const bf16_t* Z, bf16_t* MIX, const float* convw, int b, int r) {
;     ...
;     for (int k = 0; k < 3; ++k) { const f32x4 a = *(const f32x4*)(convw + k * 512 + ch), c = *(const f32x4*)(convw + k * 512 + ch + 4);
; #pragma unroll
;         for (int e = 0; e < 4; ++e) { w[k][e] = a[e]; w[k][4 + e] = c[e]; } }
; #pragma unroll 1
;     for (int half = 0; half < 2; ++half) {
;         const int s0 = r * 64 + wave * 8 + half * 4;
;         const bf16_t* base = Z + ((size_t)b * SEQ + s0) * NIN + ch;
;         const u32x4 z4 = {0u, 0u, 0u, 0u};
;         u32x4 ccw[6], cuw[6], cbw[4];
; #pragma unroll
;         for (int j = 0; j < 6; ++j) { const int s = s0 - 1 + j; const bool in = (s >= 0) && (s < SEQ); const bf16_t* p = base + (ptrdiff_t)(j - 1) * NIN;
;             ccw[j] = in ? *(const u32x4*)(p + 2048) : z4; cuw[j] = in ? *(const u32x4*)(p + 2560) : z4; }
; #pragma unroll
;         for (int j = 0; j < 4; ++j) cbw[j] = *(const u32x4*)(base + (size_t)j * NIN + 1536);
;         float u[6][8];
; #pragma unroll
;         for (int j = 0; j < 6; ++j) { float c8[8], u8[8]; unpack8(ccw[j], c8); unpack8(cuw[j], u8);
; #pragma unroll
;             for (int e = 0; e < 8; ++e) u[j][e] = c8[e] * u8[e]; }
	s_nop 0
	v_lshlrev_b32_e32 v0, 3, v24
	v_and_b32_e32 v25, 0x1f8, v0
	v_lshlrev_b32_e32 v192, 2, v25
	v_lshl_add_u64 v[12:13], s[4:5], 0, v[192:193]
	v_lshl_add_u64 v[4:5], v[12:13], 0, s[0:1]
	s_movk_i32 s0, 0x1000
	v_add_co_u32_e32 v12, vcc, s0, v12
	global_load_dwordx4 v[0:3], v192, s[4:5] offset:16
	s_nop 0
	v_addc_co_u32_e32 v13, vcc, 0, v13, vcc
	global_load_dwordx4 v[4:7], v[4:5], off offset:16 nt
	s_nop 0
	global_load_dwordx4 v[8:11], v192, s[4:5]
	s_nop 0
	global_load_dwordx4 v[12:15], v[12:13], off nt
	s_nop 0
	global_load_dwordx4 v[16:19], v192, s[4:5] offset:2064
	global_load_dwordx4 v[20:23], v192, s[4:5] offset:2048
	v_ashrrev_i32_e32 v24, 3, v24
	v_and_b32_e32 v24, -8, v24
	v_readlane_b32 s1, v255, 34
	v_lshlrev_b32_e32 v192, 1, v25
	v_xor_b32_e32 v25, 1, v236
	v_add_u32_e32 v150, s1, v24
	v_and_b32_e32 v24, 64, v236
	v_add_u32_e32 v24, 64, v24
	v_cmp_lt_i32_e32 vcc, v25, v24
	v_lshl_add_u64 v[80:81], s[72:73], 0, v[192:193]
	v_cmp_gt_u32_e64 s[4:5], s0, v150
	v_cndmask_b32_e32 v25, v236, v25, vcc
	v_lshlrev_b32_e32 v151, 2, v25
	v_xor_b32_e32 v25, 2, v236
	v_cmp_lt_i32_e32 vcc, v25, v24
	v_lshl_add_u64 v[130:131], s[74:75], 0, v[192:193]
	s_mov_b64 s[0:1], -1
	v_cndmask_b32_e32 v25, v236, v25, vcc
	v_lshlrev_b32_e32 v152, 2, v25
	v_xor_b32_e32 v25, 4, v236
	v_cmp_lt_i32_e32 vcc, v25, v24
	s_waitcnt vmcnt(5)
	v_mov_b32_e32 v82, v2
	v_cndmask_b32_e32 v25, v236, v25, vcc
	v_lshlrev_b32_e32 v153, 2, v25
	v_xor_b32_e32 v25, 8, v236
	v_cmp_lt_i32_e32 vcc, v25, v24
	s_waitcnt vmcnt(4)
	v_mov_b32_e32 v83, v6
	v_mov_b32_e32 v84, v3
	v_cndmask_b32_e32 v25, v236, v25, vcc
	v_lshlrev_b32_e32 v154, 2, v25
	v_xor_b32_e32 v25, 16, v236
	v_cmp_lt_i32_e32 vcc, v25, v24
	v_mov_b32_e32 v85, v7
	v_mov_b32_e32 v86, v0
	v_cndmask_b32_e32 v25, v236, v25, vcc
	v_lshlrev_b32_e32 v155, 2, v25
	v_xor_b32_e32 v25, 32, v236
	v_cmp_lt_i32_e32 vcc, v25, v24
	v_mov_b32_e32 v87, v4
	v_mov_b32_e32 v88, v1
	v_cndmask_b32_e32 v24, v236, v25, vcc
	v_lshlrev_b32_e32 v156, 2, v24
	v_mov_b32_e32 v89, v5
	s_waitcnt vmcnt(3)
	v_mov_b32_e32 v90, v10
	s_waitcnt vmcnt(2)
	v_mov_b32_e32 v91, v14
	v_mov_b32_e32 v92, v11
	v_mov_b32_e32 v93, v15
	v_mov_b32_e32 v94, v8
	v_mov_b32_e32 v95, v12
	v_mov_b32_e32 v96, v9
	v_mov_b32_e32 v97, v13
	v_mov_b32_e32 v98, v2
	s_waitcnt vmcnt(1)
	v_mov_b32_e32 v99, v18
	v_mov_b32_e32 v100, v3
	v_mov_b32_e32 v101, v19
	v_mov_b32_e32 v102, v0
	v_mov_b32_e32 v103, v16
	v_mov_b32_e32 v104, v1
	v_mov_b32_e32 v105, v17
	v_mov_b32_e32 v106, v10
	s_waitcnt vmcnt(0)
	v_mov_b32_e32 v107, v22
	v_mov_b32_e32 v108, v11
	v_mov_b32_e32 v109, v23
	v_mov_b32_e32 v110, v8
	v_mov_b32_e32 v111, v20
	v_mov_b32_e32 v112, v9
	v_mov_b32_e32 v113, v21
	v_mov_b32_e32 v114, v18
	v_mov_b32_e32 v115, v6
	v_mov_b32_e32 v116, v19
	v_mov_b32_e32 v117, v7
	v_mov_b32_e32 v118, v16
	v_mov_b32_e32 v119, v4
	v_mov_b32_e32 v120, v17
	v_mov_b32_e32 v121, v5
	v_mov_b32_e32 v122, v22
	v_mov_b32_e32 v123, v14
	v_mov_b32_e32 v124, v23
	v_mov_b32_e32 v125, v15
	v_mov_b32_e32 v126, v20
	v_mov_b32_e32 v127, v12
	v_mov_b32_e32 v128, v21
	v_mov_b32_e32 v129, v13
	s_branch .LBB0_300
.LBB0_299:
	s_or_b64 exec, exec, s[6:7]
	global_load_dwordx4 v[158:161], v[40:41], off offset:3072 nt
	v_add_co_u32_e32 v42, vcc, 0x2000, v40
	s_waitcnt vmcnt(1)
	v_lshlrev_b32_e32 v166, 16, v52
	v_addc_co_u32_e32 v43, vcc, 0, v41, vcc
	v_add_co_u32_e32 v48, vcc, 0x3000, v40
	v_and_b32_e32 v170, 0xffff0000, v52
	s_nop 0
	v_addc_co_u32_e32 v49, vcc, 0, v41, vcc
	global_load_dwordx4 v[162:165], v[42:43], off offset:1024 nt
	s_nop 0
	global_load_dwordx4 v[48:51], v[48:49], off offset:3072 nt
	v_add_co_u32_e32 v40, vcc, 0x5000, v40
	v_lshlrev_b32_e32 v176, 16, v53
	s_nop 0
	v_addc_co_u32_e32 v41, vcc, 0, v41, vcc
	global_load_dwordx4 v[40:43], v[40:41], off offset:1024 nt
	v_and_b32_e32 v178, 0xffff0000, v53
	v_lshlrev_b32_e32 v184, 16, v46
	v_and_b32_e32 v188, 0xffff0000, v46
	v_lshlrev_b32_e32 v190, 16, v47
	v_and_b32_e32 v148, 0xffff0000, v47
	v_lshlrev_b32_e32 v185, 16, v58
	v_and_b32_e32 v189, 0xffff0000, v58
	v_lshlrev_b32_e32 v191, 16, v59
	v_and_b32_e32 v149, 0xffff0000, v59
	v_lshlrev_b32_e32 v183, 16, v62
	v_and_b32_e32 v187, 0xffff0000, v62
	v_lshlrev_b32_e32 v195, 16, v63
	v_and_b32_e32 v147, 0xffff0000, v63
	v_lshlrev_b32_e32 v142, 16, v72
	v_lshlrev_b32_e32 v144, 16, v68
	v_and_b32_e32 v138, 0xffff0000, v72
	v_and_b32_e32 v140, 0xffff0000, v68
	v_lshlrev_b32_e32 v134, 16, v69
	v_lshlrev_b32_e32 v136, 16, v73
	v_and_b32_e32 v68, 0xffff0000, v73
	v_and_b32_e32 v72, 0xffff0000, v69
	v_lshlrev_b32_e32 v62, 16, v70
	v_and_b32_e32 v58, 0xffff0000, v70
	v_lshlrev_b32_e32 v52, 16, v71
	v_and_b32_e32 v46, 0xffff0000, v71
	v_lshlrev_b32_e32 v145, 16, v64
	v_and_b32_e32 v141, 0xffff0000, v64
	v_lshlrev_b32_e32 v135, 16, v65
	v_and_b32_e32 v73, 0xffff0000, v65
	v_lshlrev_b32_e32 v63, 16, v66
	v_and_b32_e32 v59, 0xffff0000, v66
	v_lshlrev_b32_e32 v53, 16, v67
	v_and_b32_e32 v47, 0xffff0000, v67
	v_lshlrev_b32_e32 v143, 16, v76
	v_and_b32_e32 v139, 0xffff0000, v76
	v_lshlrev_b32_e32 v137, 16, v77
	v_and_b32_e32 v69, 0xffff0000, v77
	v_lshlrev_b32_e32 v65, 16, v32
	v_lshlrev_b32_e32 v64, 16, v24
	v_lshlrev_b32_e32 v67, 16, v36
	v_lshlrev_b32_e32 v66, 16, v28
	v_and_b32_e32 v71, 0xffff0000, v32
	v_and_b32_e32 v70, 0xffff0000, v24
	v_lshlrev_b32_e32 v76, 16, v25
	v_lshlrev_b32_e32 v77, 16, v33
	v_and_b32_e32 v33, 0xffff0000, v33
	v_and_b32_e32 v32, 0xffff0000, v25
	v_and_b32_e32 v25, 0xffff0000, v37
	v_and_b32_e32 v24, 0xffff0000, v29
	v_lshlrev_b32_e32 v168, 16, v44
	v_lshlrev_b32_e32 v169, 16, v56
	v_lshlrev_b32_e32 v167, 16, v60
	v_pk_mul_f32 v[64:65], v[64:65], v[66:67]
	v_pk_mul_f32 v[24:25], v[32:33], v[24:25]
	v_lshlrev_b32_e32 v33, 16, v34
	v_lshlrev_b32_e32 v32, 16, v26
	v_lshlrev_b32_e32 v200, 16, v27
	v_lshlrev_b32_e32 v201, 16, v35
	v_and_b32_e32 v35, 0xffff0000, v35
	v_pk_mul_f32 v[66:67], v[94:95], v[64:65]
	v_lshlrev_b32_e32 v174, 16, v45
	v_and_b32_e32 v180, 0xffff0000, v45
	s_waitcnt vmcnt(3)
; __device__ __forceinline__ void unpack8(const u32x4 w, float* f) { f[0] = bf_lo(w.x); f[1] = bf_hi(w.x); f[2] = bf_lo(w.y); f[3] = bf_hi(w.y); f[4] = bf_lo(w.z); f[5] = bf_hi(w.z); f[6] = bf_lo(w.w); f[7] = bf_hi(w.w); }
; __device__ __forceinline__ void mixer_conv(const bf16_t* Z, bf16_t* MIX, const float* convw, int b, int r) {
;     ...
;         float u[6][8];
; #pragma unroll
;         for (int j = 0; j < 6; ++j) { float c8[8], u8[8]; unpack8(ccw[j], c8); unpack8(cuw[j], u8);
; #pragma unroll
;             for (int e = 0; e < 8; ++e) u[j][e] = c8[e] * u8[e]; }
;         float cv[4][8], ss[4];
; #pragma unroll
;         for (int j = 0; j < 4; ++j) { float cb[8]; unpack8(cbw[j], cb); ss[j] = 0.f;
; #pragma unroll
;             for (int e = 0; e < 8; ++e) { cv[j][e] = cb[e] * (w[0][e] * u[j][e] + w[1][e] * u[j + 1][e] + w[2][e] * u[j + 2][e]); ss[j] += cv[j][e] * cv[j][e]; } }
	v_lshlrev_b32_e32 v157, 16, v158
	v_and_b32_e32 v192, 0xffff0000, v158
	v_lshlrev_b32_e32 v204, 16, v159
	v_and_b32_e32 v205, 0xffff0000, v159
	v_and_b32_e32 v159, 0xffff0000, v34
	v_and_b32_e32 v158, 0xffff0000, v26
	v_and_b32_e32 v34, 0xffff0000, v27
	v_and_b32_e32 v27, 0xffff0000, v39
	v_and_b32_e32 v26, 0xffff0000, v31
	v_pk_mul_f32 v[26:27], v[34:35], v[26:27]
	v_pk_mul_f32 v[34:35], v[166:167], v[168:169]
	v_lshlrev_b32_e32 v194, 16, v55
	v_and_b32_e32 v146, 0xffff0000, v55
	v_lshlrev_b32_e32 v55, 16, v79
	v_and_b32_e32 v45, 0xffff0000, v79
	v_lshlrev_b32_e32 v208, 16, v161
	v_and_b32_e32 v209, 0xffff0000, v161
	v_lshlrev_b32_e32 v79, 16, v37
	v_lshlrev_b32_e32 v37, 16, v38
	v_and_b32_e32 v161, 0xffff0000, v38
	v_fma_f32 v38, v20, v34, v66
	v_add_f32_e32 v38, v38, v67
	v_and_b32_e32 v172, 0xffff0000, v44
	v_lshlrev_b32_e32 v182, 16, v54
	v_and_b32_e32 v186, 0xffff0000, v54
	v_and_b32_e32 v173, 0xffff0000, v56
	v_and_b32_e32 v171, 0xffff0000, v60
	v_lshlrev_b32_e32 v60, 16, v74
	v_and_b32_e32 v56, 0xffff0000, v74
	v_lshlrev_b32_e32 v54, 16, v75
	v_and_b32_e32 v44, 0xffff0000, v75
	v_and_b32_e32 v75, 0xffff0000, v36
	v_and_b32_e32 v74, 0xffff0000, v28
	v_lshlrev_b32_e32 v203, 16, v39
	v_mul_f32_e32 v157, v38, v157
	v_pk_mul_f32 v[38:39], v[94:95], v[34:35]
	v_pk_mul_f32 v[70:71], v[70:71], v[74:75]
	v_lshlrev_b32_e32 v36, 16, v30
	v_fma_f32 v34, v20, v65, v38
	v_lshlrev_b32_e32 v175, 16, v57
	v_and_b32_e32 v181, 0xffff0000, v57
	v_lshlrev_b32_e32 v177, 16, v61
	v_and_b32_e32 v179, 0xffff0000, v61
	v_lshlrev_b32_e32 v61, 16, v78
	v_and_b32_e32 v57, 0xffff0000, v78
	v_pk_mul_f32 v[74:75], v[96:97], v[70:71]
	v_lshlrev_b32_e32 v78, 16, v29
	v_pk_mul_f32 v[28:29], v[92:93], v[24:25]
	v_pk_mul_f32 v[32:33], v[32:33], v[36:37]
	s_waitcnt vmcnt(2)
	v_lshlrev_b32_e32 v24, 16, v162
	v_add_f32_e32 v34, v34, v39
	v_pk_mul_f32 v[38:39], v[170:171], v[172:173]
	v_pk_mul_f32 v[36:37], v[86:87], v[32:33]
	v_lshlrev_b32_e32 v32, 16, v163
	v_and_b32_e32 v64, 0xffff0000, v163
	v_mul_f32_e32 v163, v34, v24
	v_fma_f32 v24, v21, v38, v74
	v_pk_mul_f32 v[76:77], v[76:77], v[78:79]
	v_add_f32_e32 v24, v24, v75
	v_pk_mul_f32 v[66:67], v[96:97], v[38:39]
	v_pk_mul_f32 v[78:79], v[90:91], v[76:77]
	v_lshlrev_b32_e32 v70, 16, v164
	v_and_b32_e32 v76, 0xffff0000, v164
	v_mul_f32_e32 v164, v24, v192
	v_fma_f32 v24, v21, v71, v66
	v_lshlrev_b32_e32 v206, 16, v160
	v_and_b32_e32 v207, 0xffff0000, v160
	v_and_b32_e32 v160, 0xffff0000, v30
	v_lshlrev_b32_e32 v202, 16, v31
	v_pk_mul_f32 v[30:31], v[84:85], v[26:27]
	v_and_b32_e32 v26, 0xffff0000, v162
	v_add_f32_e32 v24, v24, v67
	v_pk_mul_f32 v[66:67], v[176:177], v[174:175]
	v_mul_f32_e32 v166, v24, v26
	v_fma_f32 v24, v22, v66, v78
	v_add_f32_e32 v24, v24, v79
	v_pk_mul_f32 v[74:75], v[90:91], v[66:67]
	v_mul_f32_e32 v167, v24, v204
	v_fma_f32 v24, v22, v77, v74
	v_add_f32_e32 v24, v24, v75
	v_pk_mul_f32 v[74:75], v[178:179], v[180:181]
	v_mul_f32_e32 v32, v24, v32
	v_fma_f32 v24, v23, v74, v28
	v_add_f32_e32 v24, v24, v29
	v_pk_mul_f32 v[28:29], v[92:93], v[74:75]
	v_mul_f32_e32 v168, v24, v205
	v_fma_f32 v24, v23, v25, v28
	v_add_f32_e32 v24, v24, v29
	v_pk_mul_f32 v[28:29], v[182:183], v[184:185]
	v_mul_f32_e32 v64, v24, v64
	v_fma_f32 v24, v16, v28, v36
	v_add_f32_e32 v24, v24, v37
	v_pk_mul_f32 v[36:37], v[86:87], v[28:29]
	v_pk_mul_f32 v[158:159], v[158:159], v[160:161]
	v_mul_f32_e32 v169, v24, v206
	v_fma_f32 v24, v16, v33, v36
	v_pk_mul_f32 v[160:161], v[88:89], v[158:159]
	v_add_f32_e32 v24, v24, v37
	v_pk_mul_f32 v[36:37], v[186:187], v[188:189]
	v_mul_f32_e32 v70, v24, v70
	v_fma_f32 v24, v17, v36, v160
	v_add_f32_e32 v24, v24, v161
	v_pk_mul_f32 v[78:79], v[88:89], v[36:37]
	v_pk_mul_f32 v[200:201], v[200:201], v[202:203]
	v_mul_f32_e32 v170, v24, v207
	v_fma_f32 v24, v17, v159, v78
	v_pk_mul_f32 v[202:203], v[82:83], v[200:201]
	v_add_f32_e32 v24, v24, v79
	v_pk_mul_f32 v[78:79], v[194:195], v[190:191]
	v_mul_f32_e32 v76, v24, v76
	v_fma_f32 v24, v18, v78, v202
	v_add_f32_e32 v24, v24, v203
	v_pk_mul_f32 v[160:161], v[82:83], v[78:79]
	v_mul_f32_e32 v171, v24, v208
	v_fma_f32 v24, v18, v201, v160
	v_lshlrev_b32_e32 v158, 16, v165
	v_add_f32_e32 v24, v24, v161
	v_pk_mul_f32 v[146:147], v[146:147], v[148:149]
	v_mul_f32_e32 v158, v24, v158
	v_fma_f32 v24, v19, v146, v30
	v_add_f32_e32 v24, v24, v31
	v_pk_mul_f32 v[30:31], v[84:85], v[146:147]
	v_mul_f32_e32 v148, v24, v209
	v_fma_f32 v24, v19, v27, v30
	v_mov_b32_e32 v34, v65
	v_add_f32_e32 v24, v24, v31
	v_pk_mul_f32 v[30:31], v[110:111], v[34:35]
	v_mov_b32_e32 v38, v71
	v_and_b32_e32 v162, 0xffff0000, v165
	v_add_f32_e32 v34, v30, v31
	v_pk_mul_f32 v[30:31], v[112:113], v[38:39]
	v_mov_b32_e32 v66, v77
	v_mov_b32_e32 v74, v25
	v_mul_f32_e32 v149, v24, v162
	v_add_f32_e32 v38, v30, v31
	v_pk_mul_f32 v[30:31], v[106:107], v[66:67]
	v_pk_mul_f32 v[24:25], v[108:109], v[74:75]
	v_mov_b32_e32 v28, v33
	v_add_f32_e32 v30, v30, v31
	v_add_f32_e32 v31, v24, v25
	v_pk_mul_f32 v[24:25], v[102:103], v[28:29]
	v_mov_b32_e32 v36, v159
	v_add_f32_e32 v28, v24, v25
	v_pk_mul_f32 v[24:25], v[104:105], v[36:37]
	v_mov_b32_e32 v78, v201
	v_add_f32_e32 v33, v24, v25
	v_pk_mul_f32 v[24:25], v[98:99], v[78:79]
	v_mov_b32_e32 v146, v27
	v_add_f32_e32 v36, v24, v25
	v_pk_mul_f32 v[24:25], v[100:101], v[146:147]
	s_waitcnt vmcnt(0)
; __device__ __forceinline__ void unpack8(const u32x4 w, float* f) { f[0] = bf_lo(w.x); f[1] = bf_hi(w.x); f[2] = bf_lo(w.y); f[3] = bf_hi(w.y); f[4] = bf_lo(w.z); f[5] = bf_hi(w.z); f[6] = bf_lo(w.w); f[7] = bf_hi(w.w); }
; __device__ __forceinline__ void mixer_conv(const bf16_t* Z, bf16_t* MIX, const float* convw, int b, int r) {
;     ...
;         float cv[4][8], ss[4];
; #pragma unroll
;         for (int j = 0; j < 4; ++j) { float cb[8]; unpack8(cbw[j], cb); ss[j] = 0.f;
; #pragma unroll
;             for (int e = 0; e < 8; ++e) { cv[j][e] = cb[e] * (w[0][e] * u[j][e] + w[1][e] * u[j + 1][e] + w[2][e] * u[j + 2][e]); ss[j] += cv[j][e] * cv[j][e]; } }
; #pragma unroll
;         for (int o = 1; o < 64; o <<= 1)
; #pragma unroll
;             for (int j = 0; j < 4; ++j) ss[j] += __shfl_xor(ss[j], o);
; #pragma unroll
;         for (int j = 0; j < 4; ++j) { const float rinv = __builtin_amdgcn_rsqf(ss[j] * (1.0f / 512.0f) + EPS);
	v_lshlrev_b32_e32 v65, 16, v40
	v_add_f32_e32 v27, v24, v25
	v_pk_mul_f32 v[24:25], v[142:143], v[144:145]
	v_and_b32_e32 v40, 0xffff0000, v40
	v_fmac_f32_e32 v34, v12, v24
	v_pk_mul_f32 v[24:25], v[126:127], v[24:25]
	v_lshlrev_b32_e32 v66, 16, v41
	v_fma_f32 v24, v8, v35, v24
	v_add_f32_e32 v24, v24, v25
	v_mul_f32_e32 v35, v24, v65
	v_pk_mul_f32 v[24:25], v[138:139], v[140:141]
	v_and_b32_e32 v41, 0xffff0000, v41
	v_fmac_f32_e32 v38, v13, v24
	v_pk_mul_f32 v[24:25], v[128:129], v[24:25]
	v_lshlrev_b32_e32 v71, 16, v42
	v_fma_f32 v24, v9, v39, v24
	v_add_f32_e32 v24, v24, v25
	v_mul_f32_e32 v39, v24, v40
	v_pk_mul_f32 v[24:25], v[136:137], v[134:135]
	v_mul_f32_e32 v165, v164, v164
	v_fmac_f32_e32 v30, v14, v24
	v_pk_mul_f32 v[24:25], v[122:123], v[24:25]
	v_fmac_f32_e32 v165, v157, v157
	v_fma_f32 v24, v10, v67, v24
	v_add_f32_e32 v24, v24, v25
	v_mul_f32_e32 v66, v24, v66
	v_pk_mul_f32 v[24:25], v[68:69], v[72:73]
	v_and_b32_e32 v42, 0xffff0000, v42
	v_fmac_f32_e32 v31, v15, v24
	v_pk_mul_f32 v[24:25], v[124:125], v[24:25]
	v_fmac_f32_e32 v165, v167, v167
	v_fma_f32 v24, v11, v75, v24
	v_add_f32_e32 v24, v24, v25
	v_mul_f32_e32 v41, v24, v41
	v_pk_mul_f32 v[24:25], v[60:61], v[62:63]
	v_fmac_f32_e32 v165, v168, v168
	v_fmac_f32_e32 v28, v4, v24
	v_pk_mul_f32 v[24:25], v[118:119], v[24:25]
	v_fmac_f32_e32 v165, v169, v169
	v_fma_f32 v24, v0, v29, v24
	v_add_f32_e32 v24, v24, v25
	v_mul_f32_e32 v61, v24, v71
	v_pk_mul_f32 v[24:25], v[56:57], v[58:59]
	v_fmac_f32_e32 v165, v170, v170
	v_fmac_f32_e32 v33, v5, v24
	v_pk_mul_f32 v[24:25], v[120:121], v[24:25]
	v_lshlrev_b32_e32 v160, 16, v48
	v_fma_f32 v24, v1, v37, v24
	v_add_f32_e32 v24, v24, v25
	v_mul_f32_e32 v37, v24, v42
	v_pk_mul_f32 v[24:25], v[54:55], v[52:53]
	v_and_b32_e32 v48, 0xffff0000, v48
	v_fmac_f32_e32 v36, v6, v24
	v_pk_mul_f32 v[24:25], v[114:115], v[24:25]
	v_lshlrev_b32_e32 v74, 16, v43
	v_fma_f32 v24, v2, v79, v24
	v_add_f32_e32 v24, v24, v25
	v_mul_f32_e32 v26, v166, v166
	v_fmac_f32_e32 v165, v171, v171
	v_mul_f32_e32 v38, v38, v48
	v_mul_f32_e32 v42, v24, v74
	v_pk_mul_f32 v[24:25], v[44:45], v[46:47]
	v_fmac_f32_e32 v26, v163, v163
	v_fmac_f32_e32 v165, v148, v148
	v_lshlrev_b32_e32 v161, 16, v49
	v_lshlrev_b32_e32 v172, 16, v51
	v_and_b32_e32 v51, 0xffff0000, v51
	v_mul_f32_e32 v34, v34, v160
	v_mul_f32_e32 v48, v38, v38
	v_mul_f32_e32 v40, v39, v39
	v_fmac_f32_e32 v27, v7, v24
	v_fmac_f32_e32 v26, v32, v32
	v_and_b32_e32 v49, 0xffff0000, v49
	v_fmac_f32_e32 v48, v34, v34
	v_fmac_f32_e32 v40, v35, v35
	v_mul_f32_e32 v65, v30, v161
	v_mul_f32_e32 v44, v27, v51
	ds_bpermute_b32 v27, v151, v165
	v_fmac_f32_e32 v26, v64, v64
	v_lshlrev_b32_e32 v162, 16, v50
	v_fmac_f32_e32 v48, v65, v65
	v_fmac_f32_e32 v40, v66, v66
	v_mul_f32_e32 v49, v31, v49
	v_fmac_f32_e32 v26, v70, v70
	v_and_b32_e32 v50, 0xffff0000, v50
	v_fmac_f32_e32 v48, v49, v49
	v_fmac_f32_e32 v40, v41, v41
	v_mul_f32_e32 v60, v28, v162
	v_pk_mul_f32 v[24:25], v[116:117], v[24:25]
	v_fmac_f32_e32 v26, v76, v76
	v_fmac_f32_e32 v48, v60, v60
	v_fmac_f32_e32 v40, v61, v61
	v_mul_f32_e32 v33, v33, v50
	v_fma_f32 v24, v3, v147, v24
	v_fmac_f32_e32 v26, v158, v158
	v_and_b32_e32 v43, 0xffff0000, v43
	v_fmac_f32_e32 v48, v33, v33
	v_fmac_f32_e32 v40, v37, v37
	v_mul_f32_e32 v36, v36, v172
	v_add_f32_e32 v24, v24, v25
	v_fmac_f32_e32 v26, v149, v149
	v_fmac_f32_e32 v48, v36, v36
	v_fmac_f32_e32 v40, v42, v42
	v_mul_f32_e32 v43, v24, v43
	s_waitcnt lgkmcnt(0)
	v_add_f32_e32 v24, v165, v27
	v_fmac_f32_e32 v48, v44, v44
	v_fmac_f32_e32 v40, v43, v43
	ds_bpermute_b32 v25, v151, v26
	ds_bpermute_b32 v29, v152, v24
	ds_bpermute_b32 v27, v151, v48
	ds_bpermute_b32 v28, v151, v40
	s_xor_b64 s[0:1], s[0:1], -1
	s_waitcnt lgkmcnt(3)
	v_add_f32_e32 v25, v26, v25
	s_waitcnt lgkmcnt(2)
	v_add_f32_e32 v24, v24, v29
	s_waitcnt lgkmcnt(1)
	v_add_f32_e32 v26, v48, v27
	s_waitcnt lgkmcnt(0)
	v_add_f32_e32 v27, v40, v28
	ds_bpermute_b32 v28, v152, v25
	ds_bpermute_b32 v31, v153, v24
	ds_bpermute_b32 v29, v152, v26
	ds_bpermute_b32 v30, v152, v27
	s_mov_b32 s2, 4
	s_waitcnt lgkmcnt(3)
	v_add_f32_e32 v25, v25, v28
	s_waitcnt lgkmcnt(2)
	v_add_f32_e32 v24, v24, v31
	s_waitcnt lgkmcnt(1)
	v_add_f32_e32 v26, v26, v29
	ds_bpermute_b32 v28, v153, v25
	ds_bpermute_b32 v31, v154, v24
	s_waitcnt lgkmcnt(2)
	v_add_f32_e32 v27, v27, v30
	ds_bpermute_b32 v29, v153, v26
	ds_bpermute_b32 v30, v153, v27
	s_waitcnt lgkmcnt(3)
	v_add_f32_e32 v25, v25, v28
	s_waitcnt lgkmcnt(2)
	v_add_f32_e32 v24, v24, v31
	ds_bpermute_b32 v28, v154, v25
	s_waitcnt lgkmcnt(2)
	v_add_f32_e32 v26, v26, v29
	ds_bpermute_b32 v31, v155, v24
	s_waitcnt lgkmcnt(2)
	v_add_f32_e32 v27, v27, v30
	ds_bpermute_b32 v29, v154, v26
	ds_bpermute_b32 v30, v154, v27
	s_waitcnt lgkmcnt(3)
	v_add_f32_e32 v25, v25, v28
	s_waitcnt lgkmcnt(2)
	v_add_f32_e32 v24, v24, v31
	ds_bpermute_b32 v28, v155, v25
	s_waitcnt lgkmcnt(2)
	v_add_f32_e32 v26, v26, v29
	ds_bpermute_b32 v31, v156, v24
	s_waitcnt lgkmcnt(2)
	v_add_f32_e32 v27, v27, v30
	ds_bpermute_b32 v29, v155, v26
	ds_bpermute_b32 v30, v155, v27
	s_waitcnt lgkmcnt(3)
	v_add_f32_e32 v25, v25, v28
	s_waitcnt lgkmcnt(2)
	v_add_f32_e32 v24, v24, v31
	ds_bpermute_b32 v28, v156, v25
	s_waitcnt lgkmcnt(2)
	v_add_f32_e32 v26, v26, v29
	v_fmamk_f32 v24, v24, 0x3b000000, v233
	s_waitcnt lgkmcnt(1)
	v_add_f32_e32 v27, v27, v30
	ds_bpermute_b32 v29, v156, v26
	v_rsq_f32_e32 v31, v24
	ds_bpermute_b32 v30, v156, v27
	s_waitcnt lgkmcnt(2)
	v_add_f32_e32 v28, v25, v28
	v_fmamk_f32 v28, v28, 0x3b000000, v233
	v_mul_f32_e32 v24, v157, v31
	v_mul_f32_e32 v25, v164, v31
	s_waitcnt lgkmcnt(1)
; __device__ __forceinline__ unsigned cvt_pk_bf16(float lo, float hi) { unsigned r; asm volatile("v_cvt_pk_bf16_f32 %0, %1, %2" : "=v"(r) : "v"(lo), "v"(hi)); return r; }
; __device__ __forceinline__ void unpack8(const u32x4 w, float* f) { f[0] = bf_lo(w.x); f[1] = bf_hi(w.x); f[2] = bf_lo(w.y); f[3] = bf_hi(w.y); f[4] = bf_lo(w.z); f[5] = bf_hi(w.z); f[6] = bf_lo(w.w); f[7] = bf_hi(w.w); }
; __device__ __forceinline__ void mixer_conv(const bf16_t* Z, bf16_t* MIX, const float* convw, int b, int r) {
;     ...
;     for (int half = 0; half < 2; ++half) {
;         const int s0 = r * 64 + wave * 8 + half * 4;
;         const bf16_t* base = Z + ((size_t)b * SEQ + s0) * NIN + ch;
;         const u32x4 z4 = {0u, 0u, 0u, 0u};
;         u32x4 ccw[6], cuw[6], cbw[4];
; #pragma unroll
;         for (int j = 0; j < 6; ++j) { const int s = s0 - 1 + j; const bool in = (s >= 0) && (s < SEQ); const bf16_t* p = base + (ptrdiff_t)(j - 1) * NIN;
;             ccw[j] = in ? *(const u32x4*)(p + 2048) : z4; cuw[j] = in ? *(const u32x4*)(p + 2560) : z4; }
; #pragma unroll
;         for (int j = 0; j < 4; ++j) cbw[j] = *(const u32x4*)(base + (size_t)j * NIN + 1536);
;         float u[6][8];
; #pragma unroll
;         for (int j = 0; j < 6; ++j) { float c8[8], u8[8]; unpack8(ccw[j], c8); unpack8(cuw[j], u8);
; #pragma unroll
;             for (int e = 0; e < 8; ++e) u[j][e] = c8[e] * u8[e]; }
;         float cv[4][8], ss[4];
; #pragma unroll
;         for (int j = 0; j < 4; ++j) { float cb[8]; unpack8(cbw[j], cb); ss[j] = 0.f;
; #pragma unroll
;             for (int e = 0; e < 8; ++e) { cv[j][e] = cb[e] * (w[0][e] * u[j][e] + w[1][e] * u[j + 1][e] + w[2][e] * u[j + 2][e]); ss[j] += cv[j][e] * cv[j][e]; } }
; #pragma unroll
;         for (int o = 1; o < 64; o <<= 1)
; #pragma unroll
;             for (int j = 0; j < 4; ++j) ss[j] += __shfl_xor(ss[j], o);
; #pragma unroll
;         for (int j = 0; j < 4; ++j) { const float rinv = __builtin_amdgcn_rsqf(ss[j] * (1.0f / 512.0f) + EPS);
;             u32x4 o; o.x = pg8::cvt_pk_bf16(cv[j][0] * rinv, cv[j][1] * rinv); o.y = pg8::cvt_pk_bf16(cv[j][2] * rinv, cv[j][3] * rinv); o.z = pg8::cvt_pk_bf16(cv[j][4] * rinv, cv[j][5] * rinv); o.w = pg8::cvt_pk_bf16(cv[j][6] * rinv, cv[j][7] * rinv);
;             *(u32x4*)(MIX + ((size_t)b * SEQ + s0 + j) * DM + 512 + ch) = o; }
	v_add_f32_e32 v40, v26, v29
	v_cvt_pk_bf16_f32 v24, v24, v25
	v_mul_f32_e32 v25, v167, v31
	v_mul_f32_e32 v26, v168, v31
	s_waitcnt lgkmcnt(0)
	v_add_f32_e32 v45, v27, v30
	v_cvt_pk_bf16_f32 v25, v25, v26
	v_mul_f32_e32 v26, v169, v31
	v_mul_f32_e32 v27, v170, v31
	v_rsq_f32_e32 v46, v28
	v_cvt_pk_bf16_f32 v26, v26, v27
	v_mul_f32_e32 v27, v171, v31
	v_mul_f32_e32 v29, v148, v31
	v_cvt_pk_bf16_f32 v27, v27, v29
	v_lshlrev_b64 v[28:29], 11, v[132:133]
	v_lshl_add_u64 v[30:31], v[130:131], 0, v[28:29]
	global_store_dwordx4 v[30:31], v[24:27], off offset:1024
	v_fmamk_f32 v31, v40, 0x3b000000, v233
	v_mul_f32_e32 v30, v149, v46
	v_mul_f32_e32 v24, v163, v46
	v_mul_f32_e32 v25, v166, v46
	v_cvt_pk_bf16_f32 v24, v24, v25
	v_mul_f32_e32 v25, v32, v46
	v_mul_f32_e32 v26, v64, v46
	v_cvt_pk_bf16_f32 v25, v25, v26
	v_mul_f32_e32 v26, v70, v46
	v_mul_f32_e32 v27, v76, v46
	v_rsq_f32_e32 v32, v31
	v_cvt_pk_bf16_f32 v26, v26, v27
	v_mul_f32_e32 v27, v158, v46
	v_cvt_pk_bf16_f32 v27, v27, v30
	v_or_b32_e32 v30, 0x800, v28
	v_mov_b32_e32 v31, v29
	v_lshl_add_u64 v[30:31], v[130:131], 0, v[30:31]
	global_store_dwordx4 v[30:31], v[24:27], off offset:1024
	v_fmamk_f32 v31, v45, 0x3b000000, v233
	v_mul_f32_e32 v30, v44, v32
	v_mul_f32_e32 v24, v34, v32
	v_mul_f32_e32 v25, v38, v32
	v_cvt_pk_bf16_f32 v24, v24, v25
	v_mul_f32_e32 v25, v65, v32
	v_mul_f32_e32 v26, v49, v32
	v_cvt_pk_bf16_f32 v25, v25, v26
	v_mul_f32_e32 v26, v60, v32
	v_mul_f32_e32 v27, v33, v32
	v_cvt_pk_bf16_f32 v26, v26, v27
	v_mul_f32_e32 v27, v36, v32
	v_rsq_f32_e32 v32, v31
	v_cvt_pk_bf16_f32 v27, v27, v30
	v_or_b32_e32 v30, 0x1000, v28
	v_mov_b32_e32 v31, v29
	v_lshl_add_u64 v[30:31], v[130:131], 0, v[30:31]
	global_store_dwordx4 v[30:31], v[24:27], off offset:1024
	v_or_b32_e32 v28, 0x1800, v28
	v_lshl_add_u64 v[28:29], v[130:131], 0, v[28:29]
	v_mul_f32_e32 v24, v35, v32
	v_mul_f32_e32 v25, v39, v32
	v_cvt_pk_bf16_f32 v24, v24, v25
	v_mul_f32_e32 v25, v66, v32
	v_mul_f32_e32 v26, v41, v32
	v_cvt_pk_bf16_f32 v25, v25, v26
	v_mul_f32_e32 v26, v61, v32
	v_mul_f32_e32 v27, v37, v32
	v_cvt_pk_bf16_f32 v26, v26, v27
	v_mul_f32_e32 v27, v42, v32
	s_andn2_b64 vcc, exec, s[0:1]
	s_mov_b64 s[0:1], 0
	v_mul_f32_e32 v30, v43, v32
	v_cvt_pk_bf16_f32 v27, v27, v30
	global_store_dwordx4 v[28:29], v[24:27], off offset:1024
	s_cbranch_vccz .LBB0_287
.LBB0_300:
	v_or_b32_e32 v42, s2, v150
	v_ashrrev_i32_e32 v43, 31, v42
	v_lshl_add_u64 v[132:133], s[88:89], 0, v[42:43]
	v_mad_u64_u32 v[40:41], s[6:7], v132, s83, v[80:81]
	v_add_u32_e32 v24, -1, v42
	v_mad_i32_i24 v41, v133, s83, v41
	v_cmp_gt_u32_e32 vcc, s10, v24
	v_mov_b32_e32 v44, 0
	v_mov_b32_e32 v24, 0
	v_mov_b32_e32 v25, 0
	v_mov_b32_e32 v26, 0
	v_mov_b32_e32 v27, 0
	v_mov_b32_e32 v28, 0
	v_mov_b32_e32 v29, 0
	v_mov_b32_e32 v30, 0
	v_mov_b32_e32 v31, 0
	s_and_saveexec_b64 s[6:7], vcc
	s_cbranch_execz .LBB0_302
	global_load_dwordx4 v[24:27], v[40:41], off offset:-2048 nt
	global_load_dwordx4 v[28:31], v[40:41], off offset:-1024 nt
.LBB0_302:
	s_or_b64 exec, exec, s[6:7]
	v_mov_b32_e32 v45, 0
	v_mov_b32_e32 v46, 0
	v_mov_b32_e32 v47, 0
	v_mov_b32_e32 v52, 0
	v_mov_b32_e32 v53, 0
	v_mov_b32_e32 v54, 0
	v_mov_b32_e32 v55, 0
	s_and_saveexec_b64 s[6:7], s[4:5]
	s_cbranch_execz .LBB0_304
	v_add_co_u32_e32 v32, vcc, 0x1000, v40
	s_nop 1
	v_addc_co_u32_e32 v33, vcc, 0, v41, vcc
	global_load_dwordx4 v[44:47], v[32:33], off nt
	global_load_dwordx4 v[52:55], v[32:33], off offset:1024 nt
.LBB0_304:
	s_or_b64 exec, exec, s[6:7]
	v_mov_b32_e32 v56, 0
	v_mov_b32_e32 v32, 0
	v_mov_b32_e32 v33, 0
	v_mov_b32_e32 v34, 0
	v_mov_b32_e32 v35, 0
	v_mov_b32_e32 v36, 0
	v_mov_b32_e32 v37, 0
	v_mov_b32_e32 v38, 0
	v_mov_b32_e32 v39, 0
	s_and_saveexec_b64 s[6:7], s[4:5]
	s_cbranch_execz .LBB0_306
	v_add_co_u32_e32 v36, vcc, 0x2000, v40
	s_nop 1
	v_addc_co_u32_e32 v37, vcc, 0, v41, vcc
	global_load_dwordx4 v[32:35], v[36:37], off offset:2048 nt
	s_nop 0
	global_load_dwordx4 v[36:39], v[36:37], off offset:3072 nt
.LBB0_306:
	s_or_b64 exec, exec, s[6:7]
	v_mov_b32_e32 v57, 0
	v_mov_b32_e32 v58, 0
	v_mov_b32_e32 v59, 0
	v_mov_b32_e32 v60, 0
	v_mov_b32_e32 v61, 0
	v_mov_b32_e32 v62, 0
	v_mov_b32_e32 v63, 0
	s_and_saveexec_b64 s[6:7], s[4:5]
	s_cbranch_execz .LBB0_308
	v_add_co_u32_e32 v48, vcc, 0x4000, v40
	s_nop 1
	v_addc_co_u32_e32 v49, vcc, 0, v41, vcc
	global_load_dwordx4 v[56:59], v[48:49], off nt
	global_load_dwordx4 v[60:63], v[48:49], off offset:1024 nt
.LBB0_308:
	s_or_b64 exec, exec, s[6:7]
	v_mov_b32_e32 v64, 0
	v_mov_b32_e32 v68, 0
	v_mov_b32_e32 v69, 0
	v_mov_b32_e32 v70, 0
	v_mov_b32_e32 v71, 0
	v_mov_b32_e32 v72, 0
	v_mov_b32_e32 v73, 0
	v_mov_b32_e32 v74, 0
	v_mov_b32_e32 v75, 0
	s_and_saveexec_b64 s[6:7], s[4:5]
	s_cbranch_execz .LBB0_310
	v_add_co_u32_e32 v48, vcc, 0x5000, v40
	s_nop 1
	v_addc_co_u32_e32 v49, vcc, 0, v41, vcc
	global_load_dwordx4 v[68:71], v[48:49], off offset:2048 nt
	global_load_dwordx4 v[72:75], v[48:49], off offset:3072 nt
.LBB0_310:
	s_or_b64 exec, exec, s[6:7]
	v_add_u32_e32 v42, 4, v42
	v_cmp_gt_u32_e32 vcc, s10, v42
	v_mov_b32_e32 v65, 0
	v_mov_b32_e32 v66, 0
	v_mov_b32_e32 v67, 0
	v_mov_b32_e32 v76, 0
	v_mov_b32_e32 v77, 0
	v_mov_b32_e32 v78, 0
	v_mov_b32_e32 v79, 0
	s_and_saveexec_b64 s[6:7], vcc
	s_cbranch_execz .LBB0_299
	v_add_co_u32_e32 v42, vcc, 0x7000, v40
	s_nop 1
	v_addc_co_u32_e32 v43, vcc, 0, v41, vcc
	global_load_dwordx4 v[64:67], v[42:43], off nt
	global_load_dwordx4 v[76:79], v[42:43], off offset:1024 nt
	s_branch .LBB0_299
